# GEMM K-loops: hipcc per-phase s_setprio flips replaced by one static s_setprio 1 for waves 4-7 (younger half), reset after the GEMM
# speedup vs baseline: 1.0094x; 1.0082x over previous
.LBB0_237:
	s_or_b64 exec, exec, s[30:31]
	v_readlane_b32 s0, v253, 8
	v_readlane_b32 s4, v253, 12
	v_readlane_b32 s5, v253, 13
	v_readlane_b32 s6, v253, 14
	v_readlane_b32 s7, v253, 15
	v_readlane_b32 s1, v253, 9
	v_readlane_b32 s2, v253, 10
	v_readlane_b32 s3, v253, 11
	s_mov_b32 s10, s6
	s_mov_b64 s[8:9], s[4:5]
	s_mov_b64 s[6:7], s[2:3]
	s_mov_b64 s[4:5], s[0:1]
	s_mov_b64 s[2:3], s[8:9]
	s_mov_b64 s[0:1], s[6:7]
	s_waitcnt lgkmcnt(0)
	s_barrier
	s_add_u32 s0, s2, 0x6400000
	v_readlane_b32 s4, v255, 19
	s_addc_u32 s1, s3, 0
	v_readlane_b32 s5, v255, 20
	s_and_b64 s[4:5], s[4:5], exec
	s_movk_i32 s4, 0x1a00
	s_cselect_b32 s26, s4, 0x1900
	s_lshr_b32 s6, s26, 8
	s_mov_b64 s[4:5], s[2:3]
	s_mul_i32 s66, s6, 0x60
	v_mov_b32_e32 v14, v224
	s_cmp_ge_i32 s70, s66
	v_readfirstlane_b32 s27, v14
	s_cbranch_scc1 .LBB0_249
	v_lshlrev_b32_e32 v0, 4, v14
	v_add_u32_e32 v1, 0x2000, v0
	v_ashrrev_i32_e32 v2, 31, v1
	v_lshrrev_b32_e32 v2, 22, v2
	v_add_u32_e32 v2, v1, v2
	v_ashrrev_i32_e32 v8, 10, v2
	v_mul_i32_i24_e32 v2, 0x400, v8
	v_sub_u32_e32 v1, v1, v2
	v_lshrrev_b32_e32 v2, 4, v1
	v_bitop3_b32 v1, v2, v1, 32 bitop3:0x6c
	v_ashrrev_i32_e32 v2, 31, v1
	v_lshrrev_b32_e32 v2, 26, v2
	v_add_u32_e32 v2, v1, v2
	v_lshlrev_b32_e32 v3, 3, v8
	v_ashrrev_i32_e32 v9, 6, v2
	v_and_b32_e32 v3, -16, v3
	v_add_u32_e32 v3, v9, v3
	v_and_b32_e32 v4, 3, v9
	s_mov_b32 s6, 0xfffe0
	v_lshrrev_b32_e32 v5, 2, v3
	v_lshlrev_b32_e32 v6, 1, v3
	v_and_b32_e32 v2, 0xc0, v2
	v_and_or_b32 v4, v3, s6, v4
	v_and_b32_e32 v5, 4, v5
	v_and_b32_e32 v6, 24, v6
	v_sub_u32_e32 v1, v1, v2
	v_or3_b32 v4, v4, v5, v6
	v_lshlrev_b32_e32 v5, 5, v8
	v_ashrrev_i16_sdwa v1, v226, sext(v1) dst_sel:DWORD dst_unused:UNUSED_PAD src0_sel:DWORD src1_sel:BYTE_0
	v_and_b32_e32 v5, 32, v5
	v_bfe_i32 v10, v1, 0, 16
	v_add_lshl_u32 v1, v5, v10, 1
	v_lshl_add_u32 v130, v4, 12, v1
	s_waitcnt vmcnt(0)
	v_lshl_add_u32 v132, v3, 12, v1
	v_bfe_i32 v1, v14, 27, 1
	v_lshrrev_b32_e32 v1, 22, v1
	v_add_u32_e32 v1, v0, v1
	v_and_b32_e32 v1, 0xfffffc00, v1
	v_sub_u32_e32 v0, v0, v1
	v_lshrrev_b32_e32 v1, 4, v0
	v_bitop3_b32 v1, v1, v0, 32 bitop3:0x6c
	v_ashrrev_i32_e32 v0, 31, v0
	v_lshrrev_b32_e32 v0, 26, v0
	v_add_u32_e32 v0, v1, v0
	v_ashrrev_i32_e32 v11, 6, v0
	v_ashrrev_i32_e32 v0, 31, v14
	v_lshrrev_b32_e32 v0, 26, v0
	v_add_u32_e32 v0, v14, v0
	v_ashrrev_i32_e32 v12, 6, v0
	v_lshlrev_b32_e32 v0, 3, v12
	v_and_b32_e32 v0, -16, v0
	v_add_u32_e32 v0, v11, v0
	v_and_b32_e32 v2, 3, v11
	s_ashr_i32 s8, s27, 6
	v_and_or_b32 v2, v0, s6, v2
	s_lshr_b32 s29, s66, 3
	v_readlane_b32 s6, v254, 42
	s_ashr_i32 s9, s27, 8
	s_lshl_b32 s28, s8, 10
	v_lshrrev_b32_e32 v3, 2, v0
	v_lshlrev_b32_e32 v4, 1, v0
	s_or_b32 s30, s29, 1
	v_readlane_b32 s7, v254, 43
	v_and_b32_e32 v3, 4, v3
	v_and_b32_e32 v4, 24, v4
	s_and_b64 s[6:7], s[6:7], exec
	v_or3_b32 v2, v2, v3, v4
	v_mul_i32_i24_e32 v4, 64, v11
	s_cselect_b32 s6, s30, s29
	s_lshr_b32 s31, s26, 5
	v_sub_u32_e32 v1, v1, v4
	v_cvt_f32_u32_e32 v4, s31
	v_lshlrev_b32_e32 v3, 5, v12
	v_ashrrev_i16_sdwa v1, v226, sext(v1) dst_sel:DWORD dst_unused:UNUSED_PAD src0_sel:DWORD src1_sel:BYTE_0
	v_and_b32_e32 v3, 32, v3
	v_bfe_i32 v13, v1, 0, 16
	v_add_lshl_u32 v1, v3, v13, 1
	v_rcp_iflag_f32_e32 v3, v4
	v_lshl_add_u32 v32, v2, 12, v1
	v_readlane_b32 s7, v254, 53
	s_sub_i32 s11, 0, s31
	v_mul_f32_e32 v2, 0x4f7ffffe, v3
	v_cvt_u32_f32_e32 v2, v2
	s_mul_i32 s6, s6, s7
	v_readlane_b32 s7, v254, 54
	s_add_i32 s6, s6, s7
	v_readfirstlane_b32 s34, v2
	s_mul_i32 s11, s11, s34
	s_mul_hi_u32 s11, s34, s11
	s_abs_i32 s10, s6
	s_add_i32 s34, s34, s11
	s_mul_hi_u32 s11, s10, s34
	s_mul_i32 s12, s11, s31
	s_sub_i32 s10, s10, s12
	s_ashr_i32 s7, s6, 31
	s_add_i32 s12, s11, 1
	s_sub_i32 s13, s10, s31
	s_cmp_ge_u32 s10, s31
	s_cselect_b32 s11, s12, s11
	s_cselect_b32 s10, s13, s10
	s_add_i32 s12, s11, 1
	s_cmp_ge_u32 s10, s31
	s_cselect_b32 s10, s12, s11
	s_xor_b32 s10, s10, s7
	s_sub_i32 s7, s10, s7
	s_lshl_b32 s10, s7, 3
	s_sub_i32 s11, 0x60, s10
	s_mul_i32 s7, s7, s31
	s_min_u32 s11, s11, 8
	s_sub_i32 s12, s6, s7
	s_sext_i32_i16 s6, s12
	v_cvt_f32_ubyte0_e32 v3, s11
	v_cvt_f32_i32_e32 v2, s6
	v_rcp_iflag_f32_e32 v4, v3
	v_lshl_add_u32 v134, v0, 12, v1
	s_ashr_i32 s6, s6, 30
	s_or_b32 s13, s6, 1
	v_mul_f32_e32 v0, v2, v4
	v_trunc_f32_e32 v0, v0
	v_fma_f32 v1, -v0, v3, v2
	v_cvt_i32_f32_e32 v0, v0
	v_cmp_ge_f32_e64 s[6:7], |v1|, v3
	s_and_b64 s[6:7], s[6:7], exec
	s_cselect_b32 s6, s13, 0
	v_readfirstlane_b32 s7, v0
	s_add_i32 s6, s7, s6
	s_mul_i32 s7, s6, s11
	s_sub_i32 s7, s12, s7
	s_sext_i32_i16 s7, s7
	s_add_i32 s12, s10, s7
	s_ashr_i32 s13, s12, 31
	s_bfe_i64 s[14:15], s[6:7], 0x100000
	s_lshl_b64 s[10:11], s[12:13], 20
	s_lshl_b64 s[14:15], s[14:15], 20
	s_add_u32 s18, s4, s14
	s_addc_u32 s19, s5, s15
	s_add_i32 s13, s28, 16
	s_add_i32 m0, s13, 0x10000
	v_mov_b32_e32 v131, v33
	global_load_lds_dwordx4 v32, s[18:19]
	s_add_i32 m0, s13, 0x12000
	s_add_u32 s20, s0, s10
	global_load_lds_dwordx4 v130, s[18:19]
	s_addc_u32 s21, s1, s11
	s_mov_b32 m0, s13
	s_add_i32 s35, s13, 0x2000
	global_load_lds_dwordx4 v134, s[20:21]
	s_mov_b32 m0, s35
	s_add_u32 s10, s18, 0x80000
	global_load_lds_dwordx4 v132, s[20:21]
	s_addc_u32 s11, s19, 0
	s_add_i32 m0, s13, 0x14000
	v_mov_b32_e32 v135, v33
	global_load_lds_dwordx4 v32, s[10:11]
	s_add_i32 m0, s13, 0x16000
	v_mov_b32_e32 v133, v33
	global_load_lds_dwordx4 v130, s[10:11]
	s_add_u32 s10, s20, 0x80000
	s_addc_u32 s11, s21, 0
	s_add_i32 s36, s13, 0x4000
	s_mov_b32 m0, s36
	s_add_i32 s37, s13, 0x6000
	global_load_lds_dwordx4 v134, s[10:11]
	s_mov_b32 m0, s37
	v_lshl_add_u64 v[6:7], s[18:19], 0, v[32:33]
	global_load_lds_dwordx4 v132, s[10:11]
	v_lshl_add_u64 v[4:5], s[18:19], 0, v[130:131]
	v_lshl_add_u64 v[2:3], s[20:21], 0, v[134:135]
	s_cmp_lg_u32 s9, 1
	v_lshl_add_u64 v[0:1], s[20:21], 0, v[132:133]
	s_cbranch_scc1 .LBB0_240
	s_setprio 1
	s_barrier

.LBB0_244:
	s_add_u32 s20, s18, 0xfff80080
	s_addc_u32 s21, s19, -1
	s_add_i32 s61, 16, 0x10000
	v_add_u32_e32 v140, s61, v143
	ds_read_b128 v[146:149], v140
	ds_read_b128 v[150:153], v140 offset:1024
	ds_read_b128 v[160:163], v140 offset:2048
	ds_read_b128 v[164:167], v140 offset:3072
	s_cmp_eq_u32 s60, 28
	s_cselect_b32 s23, s11, s21
	s_cselect_b32 s22, s56, s20
	s_cselect_b32 s21, s9, s59
	s_cselect_b32 s20, s57, s58
	v_lshl_add_u64 v[140:141], s[18:19], 0, v[138:139]
	s_add_i32 m0, s13, 0xc000
	ds_read_b128 v[168:171], v145
	ds_read_b128 v[172:175], v145 offset:1024
	ds_read_b128 v[176:179], v145 offset:2048
	ds_read_b128 v[180:183], v145 offset:3072
	ds_read_b128 v[184:187], v145 offset:4096
	ds_read_b128 v[188:191], v145 offset:5120
	ds_read_b128 v[192:195], v145 offset:6144
	ds_read_b128 v[196:199], v145 offset:7168
	global_load_lds_dwordx4 v[140:141], off
	v_lshl_add_u64 v[140:141], s[18:19], 0, v[136:137]
	s_add_i32 m0, s13, 0xe000
	s_nop 0
	global_load_lds_dwordx4 v[140:141], off
	s_waitcnt lgkmcnt(8)
	s_barrier
	s_waitcnt lgkmcnt(0)
	s_waitcnt lgkmcnt(0)
	v_mfma_f32_16x16x32_bf16 v[126:129], v[146:149], v[168:171], v[126:129]
	v_mfma_f32_16x16x32_bf16 v[122:125], v[160:163], v[168:171], v[122:125]
	v_mfma_f32_16x16x32_bf16 v[118:121], v[146:149], v[176:179], v[118:121]
	v_mfma_f32_16x16x32_bf16 v[110:113], v[160:163], v[176:179], v[110:113]
	v_mfma_f32_16x16x32_bf16 v[102:105], v[146:149], v[184:187], v[102:105]
	v_mfma_f32_16x16x32_bf16 v[94:97], v[160:163], v[184:187], v[94:97]
	v_mfma_f32_16x16x32_bf16 v[86:89], v[146:149], v[192:195], v[86:89]
	v_mfma_f32_16x16x32_bf16 v[78:81], v[160:163], v[192:195], v[78:81]
	v_mfma_f32_16x16x32_bf16 v[126:129], v[150:153], v[172:175], v[126:129]
	v_mfma_f32_16x16x32_bf16 v[122:125], v[164:167], v[172:175], v[122:125]
	v_mfma_f32_16x16x32_bf16 v[118:121], v[150:153], v[180:183], v[118:121]
	v_mfma_f32_16x16x32_bf16 v[110:113], v[164:167], v[180:183], v[110:113]
	v_mfma_f32_16x16x32_bf16 v[102:105], v[150:153], v[188:191], v[102:105]
	v_mfma_f32_16x16x32_bf16 v[94:97], v[164:167], v[188:191], v[94:97]
	v_mfma_f32_16x16x32_bf16 v[86:89], v[150:153], v[196:199], v[86:89]
	v_mfma_f32_16x16x32_bf16 v[78:81], v[164:167], v[196:199], v[78:81]
	s_barrier
	s_add_i32 s64, 16, 0x14000
	v_add_u32_e32 v140, s64, v143
	s_add_i32 s61, s61, s28
	ds_read_b128 v[200:203], v140
	ds_read_b128 v[204:207], v140 offset:1024
	ds_read_b128 v[208:211], v140 offset:2048
	ds_read_b128 v[212:215], v140 offset:3072
	v_lshl_add_u64 v[140:141], s[20:21], 0, v[32:33]
	s_mov_b32 m0, s61
	v_lshl_add_u64 v[156:157], s[20:21], 0, v[130:131]
	global_load_lds_dwordx4 v[140:141], off
	s_add_i32 m0, s61, 0x2000
	s_nop 0
	global_load_lds_dwordx4 v[156:157], off
	s_barrier
	s_waitcnt lgkmcnt(0)
	s_waitcnt lgkmcnt(0)
	v_mfma_f32_16x16x32_bf16 v[114:117], v[200:203], v[168:171], v[114:117]
	v_mfma_f32_16x16x32_bf16 v[106:109], v[208:211], v[168:171], v[106:109]
	v_mfma_f32_16x16x32_bf16 v[98:101], v[200:203], v[176:179], v[98:101]
	v_mfma_f32_16x16x32_bf16 v[90:93], v[208:211], v[176:179], v[90:93]
	v_mfma_f32_16x16x32_bf16 v[82:85], v[200:203], v[184:187], v[82:85]
	v_mfma_f32_16x16x32_bf16 v[74:77], v[208:211], v[184:187], v[74:77]
	v_mfma_f32_16x16x32_bf16 v[70:73], v[200:203], v[192:195], v[70:73]
	v_mfma_f32_16x16x32_bf16 v[66:69], v[208:211], v[192:195], v[66:69]
	v_mfma_f32_16x16x32_bf16 v[114:117], v[204:207], v[172:175], v[114:117]
	v_mfma_f32_16x16x32_bf16 v[106:109], v[212:215], v[172:175], v[106:109]
	v_mfma_f32_16x16x32_bf16 v[98:101], v[204:207], v[180:183], v[98:101]
	v_mfma_f32_16x16x32_bf16 v[90:93], v[212:215], v[180:183], v[90:93]
	v_mfma_f32_16x16x32_bf16 v[82:85], v[204:207], v[188:191], v[82:85]
	v_mfma_f32_16x16x32_bf16 v[74:77], v[212:215], v[188:191], v[74:77]
	v_mfma_f32_16x16x32_bf16 v[70:73], v[204:207], v[196:199], v[70:73]
	v_mfma_f32_16x16x32_bf16 v[66:69], v[212:215], v[196:199], v[66:69]
	s_mov_b32 m0, s13
	v_lshl_add_u64 v[158:159], s[22:23], 0, v[134:135]
	s_barrier
	ds_read_b128 v[168:171], v145 offset:16384
	ds_read_b128 v[172:175], v145 offset:17408
	ds_read_b128 v[176:179], v145 offset:18432
	ds_read_b128 v[180:183], v145 offset:19456
	ds_read_b128 v[184:187], v145 offset:20480
	ds_read_b128 v[188:191], v145 offset:21504
	ds_read_b128 v[192:195], v145 offset:22528
	ds_read_b128 v[196:199], v145 offset:23552
	global_load_lds_dwordx4 v[158:159], off
	v_lshl_add_u64 v[216:217], s[22:23], 0, v[132:133]
	s_mov_b32 m0, s35
	s_nop 0
	global_load_lds_dwordx4 v[216:217], off
	s_barrier
	s_waitcnt lgkmcnt(0)
	s_waitcnt lgkmcnt(0)
	v_mfma_f32_16x16x32_bf16 v[62:65], v[146:149], v[168:171], v[62:65]
	v_mfma_f32_16x16x32_bf16 v[58:61], v[160:163], v[168:171], v[58:61]
	v_mfma_f32_16x16x32_bf16 v[54:57], v[146:149], v[176:179], v[54:57]
	v_mfma_f32_16x16x32_bf16 v[46:49], v[160:163], v[176:179], v[46:49]
	v_mfma_f32_16x16x32_bf16 v[38:41], v[146:149], v[184:187], v[38:41]
	v_mfma_f32_16x16x32_bf16 v[28:31], v[160:163], v[184:187], v[28:31]
	v_mfma_f32_16x16x32_bf16 v[20:23], v[146:149], v[192:195], v[20:23]
	v_mfma_f32_16x16x32_bf16 v[12:15], v[160:163], v[192:195], v[12:15]
	v_mfma_f32_16x16x32_bf16 v[62:65], v[150:153], v[172:175], v[62:65]
	v_mfma_f32_16x16x32_bf16 v[58:61], v[164:167], v[172:175], v[58:61]
	v_mfma_f32_16x16x32_bf16 v[54:57], v[150:153], v[180:183], v[54:57]
	v_mfma_f32_16x16x32_bf16 v[46:49], v[164:167], v[180:183], v[46:49]
	v_mfma_f32_16x16x32_bf16 v[38:41], v[150:153], v[188:191], v[38:41]
	v_mfma_f32_16x16x32_bf16 v[28:31], v[164:167], v[188:191], v[28:31]
	v_mfma_f32_16x16x32_bf16 v[20:23], v[150:153], v[196:199], v[20:23]
	v_mfma_f32_16x16x32_bf16 v[12:15], v[164:167], v[196:199], v[12:15]
	s_barrier
	s_add_u32 s62, s20, 0x80000
	s_addc_u32 s63, s21, 0
	s_add_i32 s61, s64, s28
	v_lshl_add_u64 v[146:147], s[62:63], 0, v[32:33]
	s_mov_b32 m0, s61
	s_nop 0
	global_load_lds_dwordx4 v[146:147], off
	v_lshl_add_u64 v[146:147], s[62:63], 0, v[130:131]
	s_add_i32 m0, s61, 0x2000
	s_nop 0
	global_load_lds_dwordx4 v[146:147], off
	s_waitcnt vmcnt(6)
	s_barrier
	v_mfma_f32_16x16x32_bf16 v[50:53], v[200:203], v[168:171], v[50:53]
	v_mfma_f32_16x16x32_bf16 v[42:45], v[208:211], v[168:171], v[42:45]
	v_mfma_f32_16x16x32_bf16 v[34:37], v[200:203], v[176:179], v[34:37]
	v_mfma_f32_16x16x32_bf16 v[24:27], v[208:211], v[176:179], v[24:27]
	v_mfma_f32_16x16x32_bf16 v[16:19], v[200:203], v[184:187], v[16:19]
	v_mfma_f32_16x16x32_bf16 v[8:11], v[208:211], v[184:187], v[8:11]
	v_mfma_f32_16x16x32_bf16 v[4:7], v[200:203], v[192:195], v[4:7]
	v_mfma_f32_16x16x32_bf16 v[0:3], v[208:211], v[192:195], v[0:3]
	v_mfma_f32_16x16x32_bf16 v[50:53], v[204:207], v[172:175], v[50:53]
	v_mfma_f32_16x16x32_bf16 v[42:45], v[212:215], v[172:175], v[42:45]
	v_mfma_f32_16x16x32_bf16 v[34:37], v[204:207], v[180:183], v[34:37]
	v_mfma_f32_16x16x32_bf16 v[24:27], v[212:215], v[180:183], v[24:27]
	v_mfma_f32_16x16x32_bf16 v[16:19], v[204:207], v[188:191], v[16:19]
	v_mfma_f32_16x16x32_bf16 v[8:11], v[212:215], v[188:191], v[8:11]
	v_mfma_f32_16x16x32_bf16 v[4:7], v[204:207], v[196:199], v[4:7]
	v_mfma_f32_16x16x32_bf16 v[0:3], v[212:215], v[196:199], v[0:3]
	s_add_i32 s61, 16, 0x18000
	v_add_u32_e32 v155, s61, v143
	s_barrier
	ds_read_b128 v[146:149], v155
	ds_read_b128 v[150:153], v155 offset:1024
	ds_read_b128 v[160:163], v155 offset:2048
	ds_read_b128 v[164:167], v155 offset:3072
	s_add_u32 s22, s22, 0x80000
	s_addc_u32 s23, s23, 0
	s_mov_b32 m0, s36
	v_lshl_add_u64 v[200:201], s[22:23], 0, v[134:135]
	ds_read_b128 v[168:171], v145 offset:32768
	ds_read_b128 v[172:175], v145 offset:33792
	ds_read_b128 v[176:179], v145 offset:34816
	ds_read_b128 v[180:183], v145 offset:35840
	ds_read_b128 v[184:187], v145 offset:36864
	ds_read_b128 v[188:191], v145 offset:37888
	ds_read_b128 v[192:195], v145 offset:38912
	ds_read_b128 v[196:199], v145 offset:39936
	global_load_lds_dwordx4 v[200:201], off
	v_lshl_add_u64 v[200:201], s[22:23], 0, v[132:133]
	s_mov_b32 m0, s37
	s_nop 0
	global_load_lds_dwordx4 v[200:201], off
	s_waitcnt lgkmcnt(8)
	s_barrier
	s_waitcnt lgkmcnt(0)
	s_waitcnt lgkmcnt(0)
	v_mfma_f32_16x16x32_bf16 v[126:129], v[146:149], v[168:171], v[126:129]
	v_mfma_f32_16x16x32_bf16 v[122:125], v[160:163], v[168:171], v[122:125]
	v_mfma_f32_16x16x32_bf16 v[118:121], v[146:149], v[176:179], v[118:121]
	v_mfma_f32_16x16x32_bf16 v[110:113], v[160:163], v[176:179], v[110:113]
	v_mfma_f32_16x16x32_bf16 v[102:105], v[146:149], v[184:187], v[102:105]
	v_mfma_f32_16x16x32_bf16 v[94:97], v[160:163], v[184:187], v[94:97]
	v_mfma_f32_16x16x32_bf16 v[86:89], v[146:149], v[192:195], v[86:89]
	v_mfma_f32_16x16x32_bf16 v[78:81], v[160:163], v[192:195], v[78:81]
	v_mfma_f32_16x16x32_bf16 v[126:129], v[150:153], v[172:175], v[126:129]
	v_mfma_f32_16x16x32_bf16 v[122:125], v[164:167], v[172:175], v[122:125]
	v_mfma_f32_16x16x32_bf16 v[118:121], v[150:153], v[180:183], v[118:121]
	v_mfma_f32_16x16x32_bf16 v[110:113], v[164:167], v[180:183], v[110:113]
	v_mfma_f32_16x16x32_bf16 v[102:105], v[150:153], v[188:191], v[102:105]
	v_mfma_f32_16x16x32_bf16 v[94:97], v[164:167], v[188:191], v[94:97]
	v_mfma_f32_16x16x32_bf16 v[86:89], v[150:153], v[196:199], v[86:89]
	v_mfma_f32_16x16x32_bf16 v[78:81], v[164:167], v[196:199], v[78:81]
	s_barrier
	s_add_i32 s22, 16, 0x1c000
	s_add_i32 s23, s61, s28
	v_add_u32_e32 v155, s22, v143
	v_lshl_add_u64 v[140:141], v[140:141], 0, s[50:51]
	s_mov_b32 m0, s23
	ds_read_b128 v[200:203], v155
	ds_read_b128 v[204:207], v155 offset:1024
	ds_read_b128 v[208:211], v155 offset:2048
	ds_read_b128 v[212:215], v155 offset:3072
	global_load_lds_dwordx4 v[140:141], off
	v_lshl_add_u64 v[140:141], v[156:157], 0, s[50:51]
	s_add_i32 m0, s23, 0x2000
	s_nop 0
	global_load_lds_dwordx4 v[140:141], off
	s_barrier
	s_waitcnt lgkmcnt(0)
	s_waitcnt lgkmcnt(0)
	v_mfma_f32_16x16x32_bf16 v[114:117], v[200:203], v[168:171], v[114:117]
	v_mfma_f32_16x16x32_bf16 v[106:109], v[208:211], v[168:171], v[106:109]
	v_mfma_f32_16x16x32_bf16 v[98:101], v[200:203], v[176:179], v[98:101]
	v_mfma_f32_16x16x32_bf16 v[90:93], v[208:211], v[176:179], v[90:93]
	v_mfma_f32_16x16x32_bf16 v[82:85], v[200:203], v[184:187], v[82:85]
	v_mfma_f32_16x16x32_bf16 v[74:77], v[208:211], v[184:187], v[74:77]
	v_mfma_f32_16x16x32_bf16 v[70:73], v[200:203], v[192:195], v[70:73]
	v_mfma_f32_16x16x32_bf16 v[66:69], v[208:211], v[192:195], v[66:69]
	v_mfma_f32_16x16x32_bf16 v[114:117], v[204:207], v[172:175], v[114:117]
	v_mfma_f32_16x16x32_bf16 v[106:109], v[212:215], v[172:175], v[106:109]
	v_mfma_f32_16x16x32_bf16 v[98:101], v[204:207], v[180:183], v[98:101]
	v_mfma_f32_16x16x32_bf16 v[90:93], v[212:215], v[180:183], v[90:93]
	v_mfma_f32_16x16x32_bf16 v[82:85], v[204:207], v[188:191], v[82:85]
	v_mfma_f32_16x16x32_bf16 v[74:77], v[212:215], v[188:191], v[74:77]
	v_mfma_f32_16x16x32_bf16 v[70:73], v[204:207], v[196:199], v[70:73]
	v_mfma_f32_16x16x32_bf16 v[66:69], v[212:215], v[196:199], v[66:69]
	s_mov_b32 m0, s38
	v_lshl_add_u64 v[140:141], v[158:159], 0, s[50:51]
	s_barrier
	ds_read_b128 v[168:171], v145 offset:49152
	ds_read_b128 v[172:175], v145 offset:50176
	ds_read_b128 v[176:179], v145 offset:51200
	ds_read_b128 v[180:183], v145 offset:52224
	ds_read_b128 v[184:187], v145 offset:53248
	ds_read_b128 v[188:191], v145 offset:54272
	ds_read_b128 v[192:195], v145 offset:55296
	ds_read_b128 v[196:199], v145 offset:56320
	global_load_lds_dwordx4 v[140:141], off
	v_lshl_add_u64 v[140:141], v[216:217], 0, s[50:51]
	s_mov_b32 m0, s39
	s_nop 0
	global_load_lds_dwordx4 v[140:141], off
	s_barrier
	s_waitcnt lgkmcnt(0)
	s_waitcnt lgkmcnt(0)
	v_mfma_f32_16x16x32_bf16 v[62:65], v[146:149], v[168:171], v[62:65]
	v_mfma_f32_16x16x32_bf16 v[58:61], v[160:163], v[168:171], v[58:61]
	v_mfma_f32_16x16x32_bf16 v[54:57], v[146:149], v[176:179], v[54:57]
	v_mfma_f32_16x16x32_bf16 v[46:49], v[160:163], v[176:179], v[46:49]
	v_mfma_f32_16x16x32_bf16 v[38:41], v[146:149], v[184:187], v[38:41]
	v_mfma_f32_16x16x32_bf16 v[28:31], v[160:163], v[184:187], v[28:31]
	v_mfma_f32_16x16x32_bf16 v[20:23], v[146:149], v[192:195], v[20:23]
	v_mfma_f32_16x16x32_bf16 v[12:15], v[160:163], v[192:195], v[12:15]
	v_mfma_f32_16x16x32_bf16 v[62:65], v[150:153], v[172:175], v[62:65]
	v_mfma_f32_16x16x32_bf16 v[58:61], v[164:167], v[172:175], v[58:61]
	v_mfma_f32_16x16x32_bf16 v[54:57], v[150:153], v[180:183], v[54:57]
	v_mfma_f32_16x16x32_bf16 v[46:49], v[164:167], v[180:183], v[46:49]
	v_mfma_f32_16x16x32_bf16 v[38:41], v[150:153], v[188:191], v[38:41]
	v_mfma_f32_16x16x32_bf16 v[28:31], v[164:167], v[188:191], v[28:31]
	v_mfma_f32_16x16x32_bf16 v[20:23], v[150:153], v[196:199], v[20:23]
	v_mfma_f32_16x16x32_bf16 v[12:15], v[164:167], v[196:199], v[12:15]
	s_barrier
	s_add_u32 s20, s20, 0x80080
	s_addc_u32 s21, s21, 0
	s_add_i32 s22, s22, s28
	v_lshl_add_u64 v[140:141], s[20:21], 0, v[32:33]
	s_mov_b32 m0, s22
	s_nop 0
	global_load_lds_dwordx4 v[140:141], off
	v_lshl_add_u64 v[140:141], s[20:21], 0, v[130:131]
	s_add_i32 m0, s22, 0x2000
	s_nop 0
	global_load_lds_dwordx4 v[140:141], off
	s_waitcnt vmcnt(6)
	s_barrier
	v_mfma_f32_16x16x32_bf16 v[50:53], v[200:203], v[168:171], v[50:53]
	v_mfma_f32_16x16x32_bf16 v[42:45], v[208:211], v[168:171], v[42:45]
	v_mfma_f32_16x16x32_bf16 v[34:37], v[200:203], v[176:179], v[34:37]
	v_mfma_f32_16x16x32_bf16 v[24:27], v[208:211], v[176:179], v[24:27]
	v_mfma_f32_16x16x32_bf16 v[16:19], v[200:203], v[184:187], v[16:19]
	v_mfma_f32_16x16x32_bf16 v[8:11], v[208:211], v[184:187], v[8:11]
	v_mfma_f32_16x16x32_bf16 v[4:7], v[200:203], v[192:195], v[4:7]
	v_mfma_f32_16x16x32_bf16 v[0:3], v[208:211], v[192:195], v[0:3]
	v_mfma_f32_16x16x32_bf16 v[50:53], v[204:207], v[172:175], v[50:53]
	v_mfma_f32_16x16x32_bf16 v[42:45], v[212:215], v[172:175], v[42:45]
	v_mfma_f32_16x16x32_bf16 v[34:37], v[204:207], v[180:183], v[34:37]
	v_mfma_f32_16x16x32_bf16 v[24:27], v[212:215], v[180:183], v[24:27]
	v_mfma_f32_16x16x32_bf16 v[16:19], v[204:207], v[188:191], v[16:19]
	v_mfma_f32_16x16x32_bf16 v[8:11], v[212:215], v[188:191], v[8:11]
	v_mfma_f32_16x16x32_bf16 v[4:7], v[204:207], v[196:199], v[4:7]
	v_mfma_f32_16x16x32_bf16 v[0:3], v[212:215], v[196:199], v[0:3]
	s_add_i32 s60, s60, 2
	s_add_u32 s58, s58, 0x100
	s_addc_u32 s59, s59, 0
	s_add_u32 s18, s18, 0x100
	s_addc_u32 s19, s19, 0
	s_cmp_gt_u32 s60, 29
	s_barrier
	s_cbranch_scc0 .LBB0_244
	v_lshl_add_u32 v148, s12, 8, v142
	v_lshl_or_b32 v140, s47, 8, v144
	v_ashrrev_i32_e32 v141, 31, v140
	v_mad_i64_i32 v[146:147], s[18:19], v148, s26, 0
	v_cvt_pk_bf16_f32 v114, v114, v115
	v_cvt_pk_bf16_f32 v115, v116, v117
	v_cvt_pk_bf16_f32 v116, v106, v107
	v_or_b32_e32 v106, 16, v148
	v_lshl_add_u64 v[146:147], v[146:147], 1, s[6:7]
	v_lshlrev_b64 v[140:141], 1, v[140:141]
	v_mad_i64_i32 v[106:107], s[18:19], v106, s26, 0
	v_cvt_pk_bf16_f32 v98, v98, v99
	v_cvt_pk_bf16_f32 v99, v100, v101
	v_cvt_pk_bf16_f32 v100, v90, v91
	v_or_b32_e32 v90, 32, v148
	v_lshl_add_u64 v[146:147], v[146:147], 0, v[140:141]
	v_lshl_add_u64 v[106:107], v[106:107], 1, s[6:7]
	v_mad_i64_i32 v[90:91], s[18:19], v90, s26, 0
	v_cvt_pk_bf16_f32 v82, v82, v83
	v_cvt_pk_bf16_f32 v83, v84, v85
	v_cvt_pk_bf16_f32 v84, v74, v75
	v_or_b32_e32 v74, 48, v148
	v_cvt_pk_bf16_f32 v70, v70, v71
	v_cvt_pk_bf16_f32 v71, v72, v73
	v_cvt_pk_bf16_f32 v72, v66, v67
	v_add_u32_e32 v66, 0x80, v148
	v_cvt_pk_bf16_f32 v117, v108, v109
	global_store_dwordx4 v[146:147], v[114:117], off offset:256
	v_lshl_add_u64 v[90:91], v[90:91], 1, s[6:7]
	v_mad_i64_i32 v[74:75], s[18:19], v74, s26, 0
	v_lshl_add_u64 v[114:115], v[106:107], 0, v[140:141]
	v_mad_i64_i32 v[66:67], s[18:19], v66, s26, 0
	v_cvt_pk_bf16_f32 v50, v50, v51
	v_cvt_pk_bf16_f32 v51, v52, v53
	v_cvt_pk_bf16_f32 v52, v42, v43
	v_add_u32_e32 v42, 0x90, v148
	v_cvt_pk_bf16_f32 v126, v126, v127
	v_cvt_pk_bf16_f32 v127, v128, v129
	v_cvt_pk_bf16_f32 v128, v122, v123
	v_cvt_pk_bf16_f32 v129, v124, v125
	global_store_dwordx4 v[146:147], v[126:129], off
	v_cvt_pk_bf16_f32 v101, v92, v93
	global_store_dwordx4 v[114:115], v[98:101], off offset:256
	v_lshl_add_u64 v[74:75], v[74:75], 1, s[6:7]
	v_lshl_add_u64 v[66:67], v[66:67], 1, s[6:7]
	v_lshl_add_u64 v[98:99], v[90:91], 0, v[140:141]
	v_mad_i64_i32 v[42:43], s[18:19], v42, s26, 0
	v_cvt_pk_bf16_f32 v34, v34, v35
	v_cvt_pk_bf16_f32 v35, v36, v37
	v_cvt_pk_bf16_f32 v36, v24, v25
	v_add_u32_e32 v24, 0xa0, v148
	v_cvt_pk_bf16_f32 v106, v118, v119
	v_cvt_pk_bf16_f32 v107, v120, v121
	v_cvt_pk_bf16_f32 v108, v110, v111
	v_cvt_pk_bf16_f32 v109, v112, v113
	global_store_dwordx4 v[114:115], v[106:109], off
	v_cvt_pk_bf16_f32 v85, v76, v77
	global_store_dwordx4 v[98:99], v[82:85], off offset:256
	v_lshl_add_u64 v[66:67], v[66:67], 0, v[140:141]
	v_lshl_add_u64 v[42:43], v[42:43], 1, s[6:7]
	v_lshl_add_u64 v[82:83], v[74:75], 0, v[140:141]
	v_mad_i64_i32 v[24:25], s[18:19], v24, s26, 0
	v_cvt_pk_bf16_f32 v16, v16, v17
	v_cvt_pk_bf16_f32 v17, v18, v19
	v_cvt_pk_bf16_f32 v18, v8, v9
	v_add_u32_e32 v8, 0xb0, v148
	v_cvt_pk_bf16_f32 v90, v102, v103
	v_cvt_pk_bf16_f32 v91, v104, v105
	v_cvt_pk_bf16_f32 v92, v94, v95
	v_cvt_pk_bf16_f32 v93, v96, v97
	global_store_dwordx4 v[98:99], v[90:93], off
	v_cvt_pk_bf16_f32 v74, v86, v87
	v_cvt_pk_bf16_f32 v75, v88, v89
	v_cvt_pk_bf16_f32 v76, v78, v79
	v_cvt_pk_bf16_f32 v77, v80, v81
	global_store_dwordx4 v[82:83], v[74:77], off
	v_cvt_pk_bf16_f32 v73, v68, v69
	global_store_dwordx4 v[82:83], v[70:73], off offset:256
	v_cvt_pk_bf16_f32 v53, v44, v45
	global_store_dwordx4 v[66:67], v[50:53], off offset:256
	v_lshl_add_u64 v[24:25], v[24:25], 1, s[6:7]
	v_mad_i64_i32 v[8:9], s[18:19], v8, s26, 0
	v_lshl_add_u64 v[50:51], v[42:43], 0, v[140:141]
	v_cvt_pk_bf16_f32 v62, v62, v63
	v_cvt_pk_bf16_f32 v63, v64, v65
	v_cvt_pk_bf16_f32 v64, v58, v59
	v_cvt_pk_bf16_f32 v65, v60, v61
	global_store_dwordx4 v[66:67], v[62:65], off
	v_cvt_pk_bf16_f32 v37, v26, v27
	global_store_dwordx4 v[50:51], v[34:37], off offset:256
	v_lshl_add_u64 v[8:9], v[8:9], 1, s[6:7]
	v_cvt_pk_bf16_f32 v42, v54, v55
	v_cvt_pk_bf16_f32 v43, v56, v57
	v_cvt_pk_bf16_f32 v44, v46, v47
	v_cvt_pk_bf16_f32 v45, v48, v49
	s_nop 0
	v_lshl_add_u64 v[34:35], v[24:25], 0, v[140:141]
	global_store_dwordx4 v[50:51], v[42:45], off
	v_cvt_pk_bf16_f32 v19, v10, v11
	global_store_dwordx4 v[34:35], v[16:19], off offset:256
	s_and_b64 vcc, exec, s[2:3]
	s_mov_b32 s47, s8
	v_lshl_add_u64 v[16:17], v[8:9], 0, v[140:141]
	s_mov_b32 s12, s10
	s_mov_b64 s[18:19], s[16:17]
	s_mov_b64 s[20:21], s[14:15]
	v_cvt_pk_bf16_f32 v24, v38, v39
	v_cvt_pk_bf16_f32 v25, v40, v41
	v_cvt_pk_bf16_f32 v26, v28, v29
	v_cvt_pk_bf16_f32 v27, v30, v31
	global_store_dwordx4 v[34:35], v[24:27], off
	v_cvt_pk_bf16_f32 v8, v20, v21
	v_cvt_pk_bf16_f32 v9, v22, v23
	v_cvt_pk_bf16_f32 v10, v12, v13
	v_cvt_pk_bf16_f32 v11, v14, v15
	global_store_dwordx4 v[16:17], v[8:11], off
	v_cvt_pk_bf16_f32 v4, v4, v5
	v_cvt_pk_bf16_f32 v5, v6, v7
	v_cvt_pk_bf16_f32 v6, v0, v1
	v_cvt_pk_bf16_f32 v7, v2, v3
	global_store_dwordx4 v[16:17], v[4:7], off offset:256
	s_cbranch_vccz .LBB0_241
	s_waitcnt vmcnt(0)
	s_cmpk_gt_u32 s27, 0xff
	s_cbranch_scc1 .LBB0_248
	s_barrier

.LBB0_249:
	s_setprio 0
	v_readlane_b32 s0, v253, 8
	v_readlane_b32 s1, v253, 9
	v_readlane_b32 s2, v253, 10
	v_readlane_b32 s3, v253, 11
	v_readlane_b32 s4, v253, 12
	v_readlane_b32 s5, v253, 13
	s_mov_b64 s[38:39], s[4:5]
	s_mov_b64 s[0:1], s[2:3]
	s_getreg_b32 s0, hwreg(HW_REG_XCC_ID, 0, 4)
	s_waitcnt vmcnt(0)
	v_readlane_b32 s6, v253, 14
	v_readlane_b32 s7, v253, 15
	s_waitcnt vmcnt(0) lgkmcnt(0)
	s_barrier
	s_mov_b64 s[30:31], exec
	v_readlane_b32 s2, v253, 0
	v_readlane_b32 s3, v253, 1
	s_and_b64 s[2:3], s[30:31], s[2:3]
	s_mov_b64 exec, s[2:3]
	s_cbranch_execz .LBB0_293
	s_waitcnt vmcnt(0) expcnt(0) lgkmcnt(0)
	ds_read_b32 v2, v33
	ds_read_b32 v0, v33 offset:4
	s_and_b32 s66, s0, 15
	s_waitcnt lgkmcnt(1)
	v_cmp_ne_u32_e32 vcc, 0, v2
	s_cbranch_vccnz .LBB0_264
	s_add_u32 s0, s38, 0x300ae900
	s_addc_u32 s1, s39, 0
	s_add_u32 s2, s38, 0x300aeb00
	s_addc_u32 s3, s39, 0
	s_add_u32 s4, s38, 0x300aec00
	s_addc_u32 s5, s39, 0
	s_add_u32 s6, s38, 0x300aed00
	s_addc_u32 s7, s39, 0
	s_add_u32 s8, s38, 0x300aee00
	s_addc_u32 s9, s39, 0
	s_add_u32 s10, s38, 0x300aef00
	s_addc_u32 s11, s39, 0
	s_add_u32 s12, s38, 0x300af000
	s_addc_u32 s13, s39, 0
	s_add_u32 s14, s38, 0x300af100
	s_addc_u32 s15, s39, 0
	s_add_u32 s16, s38, 0x300af200
	s_addc_u32 s17, s39, 0
	s_add_u32 s18, s38, 0x300af300
	s_addc_u32 s19, s39, 0
	s_add_u32 s20, s38, 0x300af400
	s_addc_u32 s21, s39, 0
	s_add_u32 s22, s38, 0x300af500
	s_addc_u32 s23, s39, 0
	s_add_u32 s28, s38, 0x300af600
	v_writelane_b32 v255, s30, 30
	s_addc_u32 s29, s39, 0
	s_mov_b32 s84, 1
	v_writelane_b32 v255, s31, 31
	s_add_u32 s30, s38, 0x300af700
	s_addc_u32 s31, s39, 0
	s_add_u32 s34, s38, 0x300af800
	s_addc_u32 s35, s39, 0
	s_add_u32 s60, s38, 0x300af900
	s_addc_u32 s61, s39, 0
	s_add_u32 s64, s38, 0x300afa00
	s_addc_u32 s65, s39, 0
	s_mov_b64 s[46:47], 0
	s_branch .LBB0_254

.LBB0_979:
	v_readlane_b32 s0, v253, 8
	v_readlane_b32 s4, v253, 12
	v_readlane_b32 s5, v253, 13
	v_readlane_b32 s6, v253, 14
	v_readlane_b32 s7, v253, 15
	v_readlane_b32 s1, v253, 9
	v_readlane_b32 s2, v253, 10
	v_readlane_b32 s3, v253, 11
	s_mov_b32 s10, s6
	s_mov_b64 s[8:9], s[4:5]
	s_mov_b64 s[6:7], s[2:3]
	s_mov_b64 s[4:5], s[0:1]
	v_readlane_b32 s4, v255, 26
	s_mov_b64 s[2:3], s[8:9]
	s_mov_b64 s[0:1], s[6:7]
	v_readlane_b32 s5, v255, 27
	s_add_u32 s6, s2, 0x6400000
	s_mov_b32 s5, s67
	v_readlane_b32 s8, v253, 16
	s_addc_u32 s7, s3, 0
	s_lshl_b64 s[4:5], s[4:5], 2
	v_readlane_b32 s22, v253, 30
	v_readlane_b32 s23, v253, 31
	s_add_u32 s87, s22, s4
	s_addc_u32 s84, s23, s5
	v_readlane_b32 s4, v254, 40
	v_readlane_b32 s9, v253, 17
	s_add_u32 s8, s2, 0x1a00000
	v_readlane_b32 s5, v254, 41
	s_addc_u32 s9, s3, 0
	v_mov_b32_e32 v14, v224
	v_cndmask_b32_e64 v0, 0, 1, s[4:5]
	v_cmp_ne_u32_e64 s[76:77], 1, v0
	s_andn2_b64 vcc, exec, s[4:5]
	v_readfirstlane_b32 s26, v14
	v_readlane_b32 s10, v253, 18
	v_readlane_b32 s11, v253, 19
	v_readlane_b32 s12, v253, 20
	v_readlane_b32 s13, v253, 21
	v_readlane_b32 s14, v253, 22
	v_readlane_b32 s15, v253, 23
	v_readlane_b32 s16, v253, 24
	v_readlane_b32 s17, v253, 25
	v_readlane_b32 s18, v253, 26
	v_readlane_b32 s19, v253, 27
	v_readlane_b32 s20, v253, 28
	v_readlane_b32 s21, v253, 29
	s_cbranch_vccnz .LBB0_993
	v_lshlrev_b32_e32 v0, 4, v14
	v_add_u32_e32 v1, 0x2000, v0
	v_ashrrev_i32_e32 v2, 31, v1
	v_lshrrev_b32_e32 v2, 22, v2
	v_add_u32_e32 v2, v1, v2
	v_ashrrev_i32_e32 v8, 10, v2
	v_mul_i32_i24_e32 v3, 0x400, v8
	v_sub_u32_e32 v1, v1, v3
	v_lshrrev_b32_e32 v3, 4, v1
	v_bitop3_b32 v1, v3, v1, 32 bitop3:0x6c
	v_ashrrev_i32_e32 v3, 31, v1
	v_lshrrev_b32_e32 v3, 26, v3
	v_add_u32_e32 v3, v1, v3
	v_ashrrev_i32_e32 v9, 6, v3
	v_and_b32_e32 v3, 0xc0, v3
	v_sub_u32_e32 v1, v1, v3
	v_lshlrev_b32_e32 v2, 5, v8
	v_ashrrev_i16_sdwa v1, v226, sext(v1) dst_sel:DWORD dst_unused:UNUSED_PAD src0_sel:DWORD src1_sel:BYTE_0
	v_and_b32_e32 v2, 32, v2
	v_bfe_i32 v10, v1, 0, 16
	v_add_u32_e32 v1, v2, v10
	v_lshlrev_b32_e32 v2, 3, v8
	v_and_b32_e32 v2, 0xffff0, v2
	v_add_lshl_u32 v2, v9, v2, 12
	v_lshl_add_u32 v130, v1, 1, v2
	v_bfe_i32 v2, v14, 27, 1
	v_lshrrev_b32_e32 v2, 22, v2
	v_add_u32_e32 v2, v0, v2
	v_and_b32_e32 v2, 0xfffffc00, v2
	v_sub_u32_e32 v0, v0, v2
	v_lshrrev_b32_e32 v2, 4, v0
	v_bitop3_b32 v2, v2, v0, 32 bitop3:0x6c
	v_ashrrev_i32_e32 v0, 31, v0
	v_lshrrev_b32_e32 v0, 26, v0
	v_ashrrev_i32_e32 v1, 31, v14
	v_add_u32_e32 v0, v2, v0
	v_lshrrev_b32_e32 v1, 26, v1
	v_ashrrev_i32_e32 v12, 6, v0
	v_add_u32_e32 v1, v14, v1
	v_mul_i32_i24_e32 v0, 64, v12
	v_ashrrev_i32_e32 v11, 6, v1
	v_sub_u32_e32 v0, v2, v0
	v_lshlrev_b32_e32 v1, 5, v11
	v_ashrrev_i16_sdwa v0, v226, sext(v0) dst_sel:DWORD dst_unused:UNUSED_PAD src0_sel:DWORD src1_sel:BYTE_0
	s_ashr_i32 s4, s26, 6
	v_and_b32_e32 v1, 32, v1
	v_bfe_i32 v13, v0, 0, 16
	s_ashr_i32 s5, s26, 8
	s_lshl_b32 s27, s4, 10
	v_add_u32_e32 v0, v1, v13
	v_lshlrev_b32_e32 v1, 3, v11
	v_readlane_b32 s10, v254, 49
	v_and_b32_e32 v1, 0xffff0, v1
	v_readlane_b32 s11, v254, 50
	s_add_u32 s20, s8, s10
	v_add_lshl_u32 v1, v12, v1, 12
	s_addc_u32 s21, s9, s11
	s_add_i32 s28, s27, 16
	v_lshl_add_u32 v32, v0, 1, v1
	s_add_i32 m0, s28, 0x10000
	v_readlane_b32 s10, v254, 47
	global_load_lds_dwordx4 v32, s[20:21]
	s_add_i32 m0, s28, 0x12000
	v_readlane_b32 s11, v254, 48
	s_add_u32 s22, s6, s10
	global_load_lds_dwordx4 v130, s[20:21]
	s_addc_u32 s23, s7, s11
	s_mov_b32 m0, s28
	s_add_i32 s29, s28, 0x2000
	global_load_lds_dwordx4 v32, s[22:23]
	s_mov_b32 m0, s29
	s_add_u32 s10, s20, 0x80000
	global_load_lds_dwordx4 v130, s[22:23]
	s_addc_u32 s11, s21, 0
	s_add_i32 m0, s28, 0x14000
	v_mov_b32_e32 v131, v33
	global_load_lds_dwordx4 v32, s[10:11]
	s_add_i32 m0, s28, 0x16000
	v_lshl_add_u64 v[6:7], s[20:21], 0, v[32:33]
	global_load_lds_dwordx4 v130, s[10:11]
	s_add_u32 s10, s22, 0x80000
	s_addc_u32 s11, s23, 0
	s_add_i32 s30, s28, 0x4000
	s_mov_b32 m0, s30
	s_add_i32 s31, s28, 0x6000
	global_load_lds_dwordx4 v32, s[10:11]
	s_mov_b32 m0, s31
	v_lshl_add_u64 v[4:5], s[20:21], 0, v[130:131]
	global_load_lds_dwordx4 v130, s[10:11]
	v_lshl_add_u64 v[2:3], s[22:23], 0, v[32:33]
	s_cmp_lg_u32 s5, 1
	v_lshl_add_u64 v[0:1], s[22:23], 0, v[130:131]
	s_cbranch_scc1 .LBB0_982
	s_setprio 1
	s_barrier

.LBB0_987:
	s_add_u32 s2, s20, 0xfff80080
	s_addc_u32 s3, s21, -1
	s_add_i32 s60, 16, 0x10000
	v_add_u32_e32 v148, s60, v170
	ds_read_b128 v[136:139], v148
	ds_read_b128 v[140:143], v148 offset:1024
	ds_read_b128 v[144:147], v148 offset:2048
	ds_read_b128 v[148:151], v148 offset:3072
	s_cmp_eq_u32 s59, 28
	s_cselect_b32 s23, s15, s3
	s_cselect_b32 s22, s47, s2
	s_cselect_b32 s3, s13, s58
	s_cselect_b32 s2, s56, s57
	v_lshl_add_u64 v[152:153], s[20:21], 0, v[134:135]
	s_add_i32 m0, s28, 0xc000
	ds_read_b128 v[156:159], v172
	ds_read_b128 v[160:163], v172 offset:1024
	ds_read_b128 v[164:167], v172 offset:2048
	ds_read_b128 v[174:177], v172 offset:3072
	ds_read_b128 v[178:181], v172 offset:4096
	ds_read_b128 v[182:185], v172 offset:5120
	ds_read_b128 v[186:189], v172 offset:6144
	ds_read_b128 v[190:193], v172 offset:7168
	global_load_lds_dwordx4 v[152:153], off
	v_lshl_add_u64 v[152:153], s[20:21], 0, v[132:133]
	s_add_i32 m0, s28, 0xe000
	s_nop 0
	global_load_lds_dwordx4 v[152:153], off
	s_waitcnt lgkmcnt(8)
	s_barrier
	s_waitcnt lgkmcnt(0)
	s_waitcnt lgkmcnt(0)
	v_mfma_f32_16x16x32_bf16 v[126:129], v[136:139], v[156:159], v[126:129]
	v_mfma_f32_16x16x32_bf16 v[122:125], v[144:147], v[156:159], v[122:125]
	v_mfma_f32_16x16x32_bf16 v[110:113], v[136:139], v[164:167], v[110:113]
	v_mfma_f32_16x16x32_bf16 v[106:109], v[144:147], v[164:167], v[106:109]
	v_mfma_f32_16x16x32_bf16 v[102:105], v[136:139], v[178:181], v[102:105]
	v_mfma_f32_16x16x32_bf16 v[98:101], v[144:147], v[178:181], v[98:101]
	v_mfma_f32_16x16x32_bf16 v[78:81], v[136:139], v[186:189], v[78:81]
	v_mfma_f32_16x16x32_bf16 v[74:77], v[144:147], v[186:189], v[74:77]
	v_mfma_f32_16x16x32_bf16 v[126:129], v[140:143], v[160:163], v[126:129]
	v_mfma_f32_16x16x32_bf16 v[122:125], v[148:151], v[160:163], v[122:125]
	v_mfma_f32_16x16x32_bf16 v[110:113], v[140:143], v[174:177], v[110:113]
	v_mfma_f32_16x16x32_bf16 v[106:109], v[148:151], v[174:177], v[106:109]
	v_mfma_f32_16x16x32_bf16 v[102:105], v[140:143], v[182:185], v[102:105]
	v_mfma_f32_16x16x32_bf16 v[98:101], v[148:151], v[182:185], v[98:101]
	v_mfma_f32_16x16x32_bf16 v[78:81], v[140:143], v[190:193], v[78:81]
	v_mfma_f32_16x16x32_bf16 v[74:77], v[148:151], v[190:193], v[74:77]
	s_barrier
	s_add_i32 s62, 16, 0x14000
	v_add_u32_e32 v152, s62, v170
	s_add_i32 s60, s60, s27
	ds_read_b128 v[194:197], v152
	ds_read_b128 v[198:201], v152 offset:1024
	ds_read_b128 v[202:205], v152 offset:2048
	ds_read_b128 v[206:209], v152 offset:3072
	v_lshl_add_u64 v[152:153], s[2:3], 0, v[32:33]
	s_mov_b32 m0, s60
	v_lshl_add_u64 v[168:169], s[2:3], 0, v[130:131]
	global_load_lds_dwordx4 v[152:153], off
	s_add_i32 m0, s60, 0x2000
	s_nop 0
	global_load_lds_dwordx4 v[168:169], off
	s_barrier
	s_waitcnt lgkmcnt(0)
	s_waitcnt lgkmcnt(0)
	v_mfma_f32_16x16x32_bf16 v[118:121], v[194:197], v[156:159], v[118:121]
	v_mfma_f32_16x16x32_bf16 v[114:117], v[202:205], v[156:159], v[114:117]
	v_mfma_f32_16x16x32_bf16 v[94:97], v[194:197], v[164:167], v[94:97]
	v_mfma_f32_16x16x32_bf16 v[90:93], v[202:205], v[164:167], v[90:93]
	v_mfma_f32_16x16x32_bf16 v[86:89], v[194:197], v[178:181], v[86:89]
	v_mfma_f32_16x16x32_bf16 v[82:85], v[202:205], v[178:181], v[82:85]
	v_mfma_f32_16x16x32_bf16 v[70:73], v[194:197], v[186:189], v[70:73]
	v_mfma_f32_16x16x32_bf16 v[66:69], v[202:205], v[186:189], v[66:69]
	v_mfma_f32_16x16x32_bf16 v[118:121], v[198:201], v[160:163], v[118:121]
	v_mfma_f32_16x16x32_bf16 v[114:117], v[206:209], v[160:163], v[114:117]
	v_mfma_f32_16x16x32_bf16 v[94:97], v[198:201], v[174:177], v[94:97]
	v_mfma_f32_16x16x32_bf16 v[90:93], v[206:209], v[174:177], v[90:93]
	v_mfma_f32_16x16x32_bf16 v[86:89], v[198:201], v[182:185], v[86:89]
	v_mfma_f32_16x16x32_bf16 v[82:85], v[206:209], v[182:185], v[82:85]
	v_mfma_f32_16x16x32_bf16 v[70:73], v[198:201], v[190:193], v[70:73]
	v_mfma_f32_16x16x32_bf16 v[66:69], v[206:209], v[190:193], v[66:69]
	s_mov_b32 m0, s28
	v_lshl_add_u64 v[210:211], s[22:23], 0, v[32:33]
	s_barrier
	ds_read_b128 v[156:159], v172 offset:16384
	ds_read_b128 v[160:163], v172 offset:17408
	ds_read_b128 v[164:167], v172 offset:18432
	ds_read_b128 v[174:177], v172 offset:19456
	ds_read_b128 v[178:181], v172 offset:20480
	ds_read_b128 v[182:185], v172 offset:21504
	ds_read_b128 v[186:189], v172 offset:22528
	ds_read_b128 v[190:193], v172 offset:23552
	global_load_lds_dwordx4 v[210:211], off
	v_lshl_add_u64 v[212:213], s[22:23], 0, v[130:131]
	s_mov_b32 m0, s29
	s_nop 0
	global_load_lds_dwordx4 v[212:213], off
	s_barrier
	s_waitcnt lgkmcnt(0)
	s_waitcnt lgkmcnt(0)
	v_mfma_f32_16x16x32_bf16 v[62:65], v[136:139], v[156:159], v[62:65]
	v_mfma_f32_16x16x32_bf16 v[58:61], v[144:147], v[156:159], v[58:61]
	v_mfma_f32_16x16x32_bf16 v[46:49], v[136:139], v[164:167], v[46:49]
	v_mfma_f32_16x16x32_bf16 v[42:45], v[144:147], v[164:167], v[42:45]
	v_mfma_f32_16x16x32_bf16 v[38:41], v[136:139], v[178:181], v[38:41]
	v_mfma_f32_16x16x32_bf16 v[28:31], v[144:147], v[178:181], v[28:31]
	v_mfma_f32_16x16x32_bf16 v[20:23], v[136:139], v[186:189], v[20:23]
	v_mfma_f32_16x16x32_bf16 v[12:15], v[144:147], v[186:189], v[12:15]
	v_mfma_f32_16x16x32_bf16 v[62:65], v[140:143], v[160:163], v[62:65]
	v_mfma_f32_16x16x32_bf16 v[58:61], v[148:151], v[160:163], v[58:61]
	v_mfma_f32_16x16x32_bf16 v[46:49], v[140:143], v[174:177], v[46:49]
	v_mfma_f32_16x16x32_bf16 v[42:45], v[148:151], v[174:177], v[42:45]
	v_mfma_f32_16x16x32_bf16 v[38:41], v[140:143], v[182:185], v[38:41]
	v_mfma_f32_16x16x32_bf16 v[28:31], v[148:151], v[182:185], v[28:31]
	v_mfma_f32_16x16x32_bf16 v[20:23], v[140:143], v[190:193], v[20:23]
	v_mfma_f32_16x16x32_bf16 v[12:15], v[148:151], v[190:193], v[12:15]
	s_barrier
	s_add_u32 s60, s2, 0x80000
	s_addc_u32 s61, s3, 0
	s_add_i32 s62, s62, s27
	v_lshl_add_u64 v[136:137], s[60:61], 0, v[32:33]
	s_mov_b32 m0, s62
	s_nop 0
	global_load_lds_dwordx4 v[136:137], off
	v_lshl_add_u64 v[136:137], s[60:61], 0, v[130:131]
	s_add_i32 m0, s62, 0x2000
	s_nop 0
	global_load_lds_dwordx4 v[136:137], off
	s_waitcnt vmcnt(6)
	s_barrier
	v_mfma_f32_16x16x32_bf16 v[54:57], v[194:197], v[156:159], v[54:57]
	v_mfma_f32_16x16x32_bf16 v[50:53], v[202:205], v[156:159], v[50:53]
	v_mfma_f32_16x16x32_bf16 v[34:37], v[194:197], v[164:167], v[34:37]
	v_mfma_f32_16x16x32_bf16 v[24:27], v[202:205], v[164:167], v[24:27]
	v_mfma_f32_16x16x32_bf16 v[16:19], v[194:197], v[178:181], v[16:19]
	v_mfma_f32_16x16x32_bf16 v[8:11], v[202:205], v[178:181], v[8:11]
	v_mfma_f32_16x16x32_bf16 v[4:7], v[194:197], v[186:189], v[4:7]
	v_mfma_f32_16x16x32_bf16 v[0:3], v[202:205], v[186:189], v[0:3]
	v_mfma_f32_16x16x32_bf16 v[54:57], v[198:201], v[160:163], v[54:57]
	v_mfma_f32_16x16x32_bf16 v[50:53], v[206:209], v[160:163], v[50:53]
	v_mfma_f32_16x16x32_bf16 v[34:37], v[198:201], v[174:177], v[34:37]
	v_mfma_f32_16x16x32_bf16 v[24:27], v[206:209], v[174:177], v[24:27]
	v_mfma_f32_16x16x32_bf16 v[16:19], v[198:201], v[182:185], v[16:19]
	v_mfma_f32_16x16x32_bf16 v[8:11], v[206:209], v[182:185], v[8:11]
	v_mfma_f32_16x16x32_bf16 v[4:7], v[198:201], v[190:193], v[4:7]
	v_mfma_f32_16x16x32_bf16 v[0:3], v[206:209], v[190:193], v[0:3]
	s_add_i32 s60, 16, 0x18000
	v_add_u32_e32 v148, s60, v170
	s_barrier
	ds_read_b128 v[136:139], v148
	ds_read_b128 v[140:143], v148 offset:1024
	ds_read_b128 v[144:147], v148 offset:2048
	ds_read_b128 v[148:151], v148 offset:3072
	s_add_u32 s22, s22, 0x80000
	s_addc_u32 s23, s23, 0
	s_mov_b32 m0, s30
	v_lshl_add_u64 v[194:195], s[22:23], 0, v[32:33]
	ds_read_b128 v[156:159], v172 offset:32768
	ds_read_b128 v[160:163], v172 offset:33792
	ds_read_b128 v[164:167], v172 offset:34816
	ds_read_b128 v[174:177], v172 offset:35840
	ds_read_b128 v[178:181], v172 offset:36864
	ds_read_b128 v[182:185], v172 offset:37888
	ds_read_b128 v[186:189], v172 offset:38912
	ds_read_b128 v[190:193], v172 offset:39936
	global_load_lds_dwordx4 v[194:195], off
	v_lshl_add_u64 v[194:195], s[22:23], 0, v[130:131]
	s_mov_b32 m0, s31
	s_nop 0
	global_load_lds_dwordx4 v[194:195], off
	s_waitcnt lgkmcnt(8)
	s_barrier
	s_waitcnt lgkmcnt(0)
	s_waitcnt lgkmcnt(0)
	v_mfma_f32_16x16x32_bf16 v[126:129], v[136:139], v[156:159], v[126:129]
	v_mfma_f32_16x16x32_bf16 v[122:125], v[144:147], v[156:159], v[122:125]
	v_mfma_f32_16x16x32_bf16 v[110:113], v[136:139], v[164:167], v[110:113]
	v_mfma_f32_16x16x32_bf16 v[106:109], v[144:147], v[164:167], v[106:109]
	v_mfma_f32_16x16x32_bf16 v[102:105], v[136:139], v[178:181], v[102:105]
	v_mfma_f32_16x16x32_bf16 v[98:101], v[144:147], v[178:181], v[98:101]
	v_mfma_f32_16x16x32_bf16 v[78:81], v[136:139], v[186:189], v[78:81]
	v_mfma_f32_16x16x32_bf16 v[74:77], v[144:147], v[186:189], v[74:77]
	v_mfma_f32_16x16x32_bf16 v[126:129], v[140:143], v[160:163], v[126:129]
	v_mfma_f32_16x16x32_bf16 v[122:125], v[148:151], v[160:163], v[122:125]
	v_mfma_f32_16x16x32_bf16 v[110:113], v[140:143], v[174:177], v[110:113]
	v_mfma_f32_16x16x32_bf16 v[106:109], v[148:151], v[174:177], v[106:109]
	v_mfma_f32_16x16x32_bf16 v[102:105], v[140:143], v[182:185], v[102:105]
	v_mfma_f32_16x16x32_bf16 v[98:101], v[148:151], v[182:185], v[98:101]
	v_mfma_f32_16x16x32_bf16 v[78:81], v[140:143], v[190:193], v[78:81]
	v_mfma_f32_16x16x32_bf16 v[74:77], v[148:151], v[190:193], v[74:77]
	s_barrier
	s_add_i32 s22, 16, 0x1c000
	s_add_i32 s23, s60, s27
	v_add_u32_e32 v173, s22, v170
	v_lshl_add_u64 v[152:153], v[152:153], 0, s[50:51]
	s_mov_b32 m0, s23
	ds_read_b128 v[194:197], v173
	ds_read_b128 v[198:201], v173 offset:1024
	ds_read_b128 v[202:205], v173 offset:2048
	ds_read_b128 v[206:209], v173 offset:3072
	global_load_lds_dwordx4 v[152:153], off
	v_lshl_add_u64 v[152:153], v[168:169], 0, s[50:51]
	s_add_i32 m0, s23, 0x2000
	s_nop 0
	global_load_lds_dwordx4 v[152:153], off
	s_barrier
	s_waitcnt lgkmcnt(0)
	s_waitcnt lgkmcnt(0)
	v_mfma_f32_16x16x32_bf16 v[118:121], v[194:197], v[156:159], v[118:121]
	v_mfma_f32_16x16x32_bf16 v[114:117], v[202:205], v[156:159], v[114:117]
	v_mfma_f32_16x16x32_bf16 v[94:97], v[194:197], v[164:167], v[94:97]
	v_mfma_f32_16x16x32_bf16 v[90:93], v[202:205], v[164:167], v[90:93]
	v_mfma_f32_16x16x32_bf16 v[86:89], v[194:197], v[178:181], v[86:89]
	v_mfma_f32_16x16x32_bf16 v[82:85], v[202:205], v[178:181], v[82:85]
	v_mfma_f32_16x16x32_bf16 v[70:73], v[194:197], v[186:189], v[70:73]
	v_mfma_f32_16x16x32_bf16 v[66:69], v[202:205], v[186:189], v[66:69]
	v_mfma_f32_16x16x32_bf16 v[118:121], v[198:201], v[160:163], v[118:121]
	v_mfma_f32_16x16x32_bf16 v[114:117], v[206:209], v[160:163], v[114:117]
	v_mfma_f32_16x16x32_bf16 v[94:97], v[198:201], v[174:177], v[94:97]
	v_mfma_f32_16x16x32_bf16 v[90:93], v[206:209], v[174:177], v[90:93]
	v_mfma_f32_16x16x32_bf16 v[86:89], v[198:201], v[182:185], v[86:89]
	v_mfma_f32_16x16x32_bf16 v[82:85], v[206:209], v[182:185], v[82:85]
	v_mfma_f32_16x16x32_bf16 v[70:73], v[198:201], v[190:193], v[70:73]
	v_mfma_f32_16x16x32_bf16 v[66:69], v[206:209], v[190:193], v[66:69]
	s_mov_b32 m0, s36
	v_lshl_add_u64 v[152:153], v[210:211], 0, s[50:51]
	s_barrier
	ds_read_b128 v[156:159], v172 offset:49152
	ds_read_b128 v[160:163], v172 offset:50176
	ds_read_b128 v[164:167], v172 offset:51200
	ds_read_b128 v[174:177], v172 offset:52224
	ds_read_b128 v[178:181], v172 offset:53248
	ds_read_b128 v[182:185], v172 offset:54272
	ds_read_b128 v[186:189], v172 offset:55296
	ds_read_b128 v[190:193], v172 offset:56320
	global_load_lds_dwordx4 v[152:153], off
	v_lshl_add_u64 v[152:153], v[212:213], 0, s[50:51]
	s_mov_b32 m0, s37
	s_nop 0
	global_load_lds_dwordx4 v[152:153], off
	s_barrier
	s_waitcnt lgkmcnt(0)
	s_waitcnt lgkmcnt(0)
	v_mfma_f32_16x16x32_bf16 v[62:65], v[136:139], v[156:159], v[62:65]
	v_mfma_f32_16x16x32_bf16 v[58:61], v[144:147], v[156:159], v[58:61]
	v_mfma_f32_16x16x32_bf16 v[46:49], v[136:139], v[164:167], v[46:49]
	v_mfma_f32_16x16x32_bf16 v[42:45], v[144:147], v[164:167], v[42:45]
	v_mfma_f32_16x16x32_bf16 v[38:41], v[136:139], v[178:181], v[38:41]
	v_mfma_f32_16x16x32_bf16 v[28:31], v[144:147], v[178:181], v[28:31]
	v_mfma_f32_16x16x32_bf16 v[20:23], v[136:139], v[186:189], v[20:23]
	v_mfma_f32_16x16x32_bf16 v[12:15], v[144:147], v[186:189], v[12:15]
	v_mfma_f32_16x16x32_bf16 v[62:65], v[140:143], v[160:163], v[62:65]
	v_mfma_f32_16x16x32_bf16 v[58:61], v[148:151], v[160:163], v[58:61]
	v_mfma_f32_16x16x32_bf16 v[46:49], v[140:143], v[174:177], v[46:49]
	v_mfma_f32_16x16x32_bf16 v[42:45], v[148:151], v[174:177], v[42:45]
	v_mfma_f32_16x16x32_bf16 v[38:41], v[140:143], v[182:185], v[38:41]
	v_mfma_f32_16x16x32_bf16 v[28:31], v[148:151], v[182:185], v[28:31]
	v_mfma_f32_16x16x32_bf16 v[20:23], v[140:143], v[190:193], v[20:23]
	v_mfma_f32_16x16x32_bf16 v[12:15], v[148:151], v[190:193], v[12:15]
	s_barrier
	s_add_u32 s2, s2, 0x80080
	s_addc_u32 s3, s3, 0
	s_add_i32 s22, s22, s27
	v_lshl_add_u64 v[136:137], s[2:3], 0, v[32:33]
	s_mov_b32 m0, s22
	s_nop 0
	global_load_lds_dwordx4 v[136:137], off
	v_lshl_add_u64 v[136:137], s[2:3], 0, v[130:131]
	s_add_i32 m0, s22, 0x2000
	s_nop 0
	global_load_lds_dwordx4 v[136:137], off
	s_waitcnt vmcnt(6)
	s_barrier
	v_mfma_f32_16x16x32_bf16 v[54:57], v[194:197], v[156:159], v[54:57]
	v_mfma_f32_16x16x32_bf16 v[50:53], v[202:205], v[156:159], v[50:53]
	v_mfma_f32_16x16x32_bf16 v[34:37], v[194:197], v[164:167], v[34:37]
	v_mfma_f32_16x16x32_bf16 v[24:27], v[202:205], v[164:167], v[24:27]
	v_mfma_f32_16x16x32_bf16 v[16:19], v[194:197], v[178:181], v[16:19]
	v_mfma_f32_16x16x32_bf16 v[8:11], v[202:205], v[178:181], v[8:11]
	v_mfma_f32_16x16x32_bf16 v[4:7], v[194:197], v[186:189], v[4:7]
	v_mfma_f32_16x16x32_bf16 v[0:3], v[202:205], v[186:189], v[0:3]
	v_mfma_f32_16x16x32_bf16 v[54:57], v[198:201], v[160:163], v[54:57]
	v_mfma_f32_16x16x32_bf16 v[50:53], v[206:209], v[160:163], v[50:53]
	v_mfma_f32_16x16x32_bf16 v[34:37], v[198:201], v[174:177], v[34:37]
	v_mfma_f32_16x16x32_bf16 v[24:27], v[206:209], v[174:177], v[24:27]
	v_mfma_f32_16x16x32_bf16 v[16:19], v[198:201], v[182:185], v[16:19]
	v_mfma_f32_16x16x32_bf16 v[8:11], v[206:209], v[182:185], v[8:11]
	v_mfma_f32_16x16x32_bf16 v[4:7], v[198:201], v[190:193], v[4:7]
	v_mfma_f32_16x16x32_bf16 v[0:3], v[206:209], v[190:193], v[0:3]
	s_add_i32 s59, s59, 2
	s_add_u32 s57, s57, 0x100
	s_addc_u32 s58, s58, 0
	s_add_u32 s20, s20, 0x100
	s_addc_u32 s21, s21, 0
	s_cmp_gt_u32 s59, 29
	s_barrier
	s_cbranch_scc0 .LBB0_987
	s_cmp_lt_i32 s46, 32
	s_mov_b64 s[2:3], 0xc000
	s_cbranch_scc1 .LBB0_983
	s_sub_i32 s2, s46, 32
	s_lshr_b32 s2, s2, 4
	s_mul_hi_u32 s3, s2, 0x3000
	s_mulk_i32 s2, 0x3000
	s_branch .LBB0_983

.LBB0_993:
	s_setprio 0
	v_readlane_b32 s0, v253, 8
	v_readlane_b32 s1, v253, 9
	v_readlane_b32 s2, v253, 10
	v_readlane_b32 s3, v253, 11
	v_readlane_b32 s4, v253, 12
	v_readlane_b32 s5, v253, 13
	s_mov_b64 s[64:65], s[4:5]
	s_mov_b64 s[0:1], s[2:3]
	s_getreg_b32 s0, hwreg(HW_REG_XCC_ID, 0, 4)
	s_waitcnt vmcnt(0)
	v_readlane_b32 s6, v253, 14
	v_readlane_b32 s7, v253, 15
	s_waitcnt lgkmcnt(0)
	s_barrier
	s_mov_b64 s[78:79], exec
	v_readlane_b32 s2, v253, 0
	v_readlane_b32 s3, v253, 1
	s_and_b64 s[2:3], s[78:79], s[2:3]
	s_mov_b64 exec, s[2:3]
	s_cbranch_execz .LBB0_1037
	s_waitcnt vmcnt(0) expcnt(0) lgkmcnt(0)
	ds_read_b32 v2, v33
	ds_read_b32 v0, v33 offset:4
	s_and_b32 s66, s0, 15
	s_waitcnt lgkmcnt(1)
	v_cmp_ne_u32_e32 vcc, 0, v2
	s_cbranch_vccnz .LBB0_1008
	s_add_u32 s0, s64, 0x300ae900
	s_addc_u32 s1, s65, 0
	s_add_u32 s4, s64, 0x300aeb00
	s_addc_u32 s5, s65, 0
	s_add_u32 s6, s64, 0x300aec00
	s_addc_u32 s7, s65, 0
	s_add_u32 s8, s64, 0x300aed00
	s_addc_u32 s9, s65, 0
	s_add_u32 s10, s64, 0x300aee00
	s_addc_u32 s11, s65, 0
	s_add_u32 s12, s64, 0x300aef00
	s_addc_u32 s13, s65, 0
	s_add_u32 s14, s64, 0x300af000
	s_addc_u32 s15, s65, 0
	s_add_u32 s16, s64, 0x300af100
	s_addc_u32 s17, s65, 0
	s_add_u32 s18, s64, 0x300af200
	s_addc_u32 s19, s65, 0
	s_add_u32 s20, s64, 0x300af300
	s_addc_u32 s21, s65, 0
	s_add_u32 s22, s64, 0x300af400
	s_addc_u32 s23, s65, 0
	s_add_u32 s28, s64, 0x300af500
	s_addc_u32 s29, s65, 0
	s_add_u32 s30, s64, 0x300af600
	s_addc_u32 s31, s65, 0
	s_add_u32 s34, s64, 0x300af700
	s_addc_u32 s35, s65, 0
	s_add_u32 s36, s64, 0x300af800
	s_addc_u32 s37, s65, 0
	s_add_u32 s60, s64, 0x300af900
	s_addc_u32 s61, s65, 0
	s_add_u32 s2, s64, 0x300afa00
	s_addc_u32 s3, s65, 0
	s_mov_b32 s86, 1
	s_mov_b64 s[46:47], 0
	s_branch .LBB0_998

.LBB0_1097:
	s_or_b64 exec, exec, s[78:79]
	v_readlane_b32 s0, v253, 8
	v_readlane_b32 s4, v253, 12
	v_readlane_b32 s5, v253, 13
	v_readlane_b32 s6, v253, 14
	v_readlane_b32 s7, v253, 15
	v_readlane_b32 s1, v253, 9
	v_readlane_b32 s2, v253, 10
	v_readlane_b32 s3, v253, 11
	s_mov_b32 s10, s6
	s_mov_b64 s[8:9], s[4:5]
	s_mov_b64 s[6:7], s[2:3]
	s_mov_b64 s[4:5], s[0:1]
	s_mov_b64 s[2:3], s[8:9]
	s_mov_b64 s[0:1], s[6:7]
	s_waitcnt lgkmcnt(0)
	s_barrier
	s_add_u32 s0, s2, 0x6400000
	s_addc_u32 s1, s3, 0
	s_add_u32 s6, s2, 0x2200000
	v_readlane_b32 s4, v254, 51
	s_addc_u32 s7, s3, 0
	v_mov_b32_e32 v14, v224
	v_readlane_b32 s5, v254, 52
	s_andn2_b64 vcc, exec, s[4:5]
	v_readfirstlane_b32 s22, v14
	s_cbranch_vccnz .LBB0_1109
	v_lshlrev_b32_e32 v0, 4, v14
	v_add_u32_e32 v1, 0x2000, v0
	v_ashrrev_i32_e32 v2, 31, v1
	v_lshrrev_b32_e32 v2, 22, v2
	v_add_u32_e32 v2, v1, v2
	v_ashrrev_i32_e32 v8, 10, v2
	v_mul_i32_i24_e32 v2, 0x400, v8
	v_sub_u32_e32 v1, v1, v2
	v_lshrrev_b32_e32 v2, 4, v1
	v_bitop3_b32 v1, v2, v1, 32 bitop3:0x6c
	v_ashrrev_i32_e32 v2, 31, v1
	v_lshrrev_b32_e32 v2, 26, v2
	v_add_u32_e32 v2, v1, v2
	v_lshlrev_b32_e32 v3, 3, v8
	v_ashrrev_i32_e32 v9, 6, v2
	v_and_b32_e32 v3, -16, v3
	v_add_u32_e32 v3, v9, v3
	v_and_b32_e32 v4, 3, v9
	s_mov_b32 s8, 0xfffe0
	v_lshrrev_b32_e32 v5, 2, v3
	v_lshlrev_b32_e32 v6, 1, v3
	v_and_b32_e32 v2, 0xc0, v2
	v_and_or_b32 v4, v3, s8, v4
	v_and_b32_e32 v5, 4, v5
	v_and_b32_e32 v6, 24, v6
	v_sub_u32_e32 v1, v1, v2
	v_or3_b32 v4, v4, v5, v6
	v_lshlrev_b32_e32 v5, 5, v8
	v_ashrrev_i16_sdwa v1, v226, sext(v1) dst_sel:DWORD dst_unused:UNUSED_PAD src0_sel:DWORD src1_sel:BYTE_0
	v_and_b32_e32 v5, 32, v5
	v_bfe_i32 v10, v1, 0, 16
	v_add_lshl_u32 v1, v5, v10, 1
	v_lshl_add_u32 v130, v4, 12, v1
	v_lshl_add_u32 v132, v3, 12, v1
	v_bfe_i32 v1, v14, 27, 1
	v_lshrrev_b32_e32 v1, 22, v1
	v_add_u32_e32 v1, v0, v1
	v_and_b32_e32 v1, 0xfffffc00, v1
	v_sub_u32_e32 v0, v0, v1
	v_lshrrev_b32_e32 v1, 4, v0
	v_bitop3_b32 v1, v1, v0, 32 bitop3:0x6c
	v_ashrrev_i32_e32 v0, 31, v0
	v_lshrrev_b32_e32 v0, 26, v0
	v_add_u32_e32 v0, v1, v0
	v_ashrrev_i32_e32 v11, 6, v0
	v_ashrrev_i32_e32 v0, 31, v14
	v_lshrrev_b32_e32 v0, 26, v0
	v_add_u32_e32 v0, v14, v0
	v_ashrrev_i32_e32 v12, 6, v0
	v_lshlrev_b32_e32 v0, 3, v12
	v_and_b32_e32 v0, -16, v0
	v_add_u32_e32 v0, v11, v0
	v_and_b32_e32 v2, 3, v11
	v_lshrrev_b32_e32 v3, 2, v0
	v_lshlrev_b32_e32 v4, 1, v0
	v_and_or_b32 v2, v0, s8, v2
	v_and_b32_e32 v3, 4, v3
	v_and_b32_e32 v4, 24, v4
	v_or3_b32 v2, v2, v3, v4
	v_mul_i32_i24_e32 v4, 64, v11
	s_ashr_i32 s4, s22, 6
	v_sub_u32_e32 v1, v1, v4
	s_ashr_i32 s5, s22, 8
	s_lshl_b32 s23, s4, 10
	v_lshlrev_b32_e32 v3, 5, v12
	v_ashrrev_i16_sdwa v1, v226, sext(v1) dst_sel:DWORD dst_unused:UNUSED_PAD src0_sel:DWORD src1_sel:BYTE_0
	v_readlane_b32 s8, v254, 56
	v_and_b32_e32 v3, 32, v3
	v_bfe_i32 v13, v1, 0, 16
	v_readlane_b32 s9, v254, 57
	s_add_u32 s18, s6, s8
	v_add_lshl_u32 v1, v3, v13, 1
	s_addc_u32 s19, s7, s9
	s_add_i32 s26, s23, 16
	v_lshl_add_u32 v32, v2, 12, v1
	s_add_i32 m0, s26, 0x10000
	v_readlane_b32 s8, v254, 60
	global_load_lds_dwordx4 v32, s[18:19]
	s_add_i32 m0, s26, 0x12000
	v_readlane_b32 s9, v254, 61
	s_add_u32 s20, s0, s8
	v_lshl_add_u32 v134, v0, 12, v1
	global_load_lds_dwordx4 v130, s[18:19]
	s_addc_u32 s21, s1, s9
	s_mov_b32 m0, s26
	s_add_i32 s27, s26, 0x2000
	global_load_lds_dwordx4 v134, s[20:21]
	s_mov_b32 m0, s27
	s_add_u32 s8, s18, 0x80000
	global_load_lds_dwordx4 v132, s[20:21]
	s_addc_u32 s9, s19, 0
	s_add_i32 m0, s26, 0x14000
	v_mov_b32_e32 v131, v33
	global_load_lds_dwordx4 v32, s[8:9]
	s_add_i32 m0, s26, 0x16000
	v_mov_b32_e32 v135, v33
	global_load_lds_dwordx4 v130, s[8:9]
	s_add_u32 s8, s20, 0x80000
	s_addc_u32 s9, s21, 0
	s_add_i32 s28, s26, 0x4000
	s_mov_b32 m0, s28
	s_add_i32 s29, s26, 0x6000
	global_load_lds_dwordx4 v134, s[8:9]
	s_mov_b32 m0, s29
	v_mov_b32_e32 v133, v33
	global_load_lds_dwordx4 v132, s[8:9]
	v_lshl_add_u64 v[6:7], s[18:19], 0, v[32:33]
	v_lshl_add_u64 v[4:5], s[18:19], 0, v[130:131]
	v_lshl_add_u64 v[2:3], s[20:21], 0, v[134:135]
	s_cmp_lg_u32 s5, 1
	v_lshl_add_u64 v[0:1], s[20:21], 0, v[132:133]
	s_cbranch_scc1 .LBB0_1100
	s_setprio 1
	s_barrier

.LBB0_1104:
	s_add_u32 s2, s18, 0xfff80080
	s_addc_u32 s3, s19, -1
	s_add_i32 s56, 16, 0x10000
	v_add_u32_e32 v152, s56, v145
	ds_read_b128 v[140:143], v152
	ds_read_b128 v[148:151], v152 offset:1024
	ds_read_b128 v[156:159], v152 offset:2048
	ds_read_b128 v[160:163], v152 offset:3072
	s_cmp_eq_u32 s47, 28
	s_cselect_b32 s21, s13, s3
	s_cselect_b32 s20, s37, s2
	s_cselect_b32 s3, s11, s46
	s_cselect_b32 s2, s38, s39
	v_lshl_add_u64 v[152:153], s[18:19], 0, v[138:139]
	s_add_i32 m0, s26, 0xc000
	ds_read_b128 v[164:167], v147
	ds_read_b128 v[168:171], v147 offset:1024
	ds_read_b128 v[172:175], v147 offset:2048
	ds_read_b128 v[176:179], v147 offset:3072
	ds_read_b128 v[180:183], v147 offset:4096
	ds_read_b128 v[184:187], v147 offset:5120
	ds_read_b128 v[188:191], v147 offset:6144
	ds_read_b128 v[192:195], v147 offset:7168
	global_load_lds_dwordx4 v[152:153], off
	v_lshl_add_u64 v[152:153], s[18:19], 0, v[136:137]
	s_add_i32 m0, s26, 0xe000
	s_nop 0
	global_load_lds_dwordx4 v[152:153], off
	s_waitcnt lgkmcnt(8)
	s_barrier
	s_waitcnt lgkmcnt(0)
	s_waitcnt lgkmcnt(0)
	v_mfma_f32_16x16x32_bf16 v[126:129], v[140:143], v[164:167], v[126:129]
	v_mfma_f32_16x16x32_bf16 v[122:125], v[156:159], v[164:167], v[122:125]
	v_mfma_f32_16x16x32_bf16 v[118:121], v[140:143], v[172:175], v[118:121]
	v_mfma_f32_16x16x32_bf16 v[110:113], v[156:159], v[172:175], v[110:113]
	v_mfma_f32_16x16x32_bf16 v[102:105], v[140:143], v[180:183], v[102:105]
	v_mfma_f32_16x16x32_bf16 v[94:97], v[156:159], v[180:183], v[94:97]
	v_mfma_f32_16x16x32_bf16 v[86:89], v[140:143], v[188:191], v[86:89]
	v_mfma_f32_16x16x32_bf16 v[78:81], v[156:159], v[188:191], v[78:81]
	v_mfma_f32_16x16x32_bf16 v[126:129], v[148:151], v[168:171], v[126:129]
	v_mfma_f32_16x16x32_bf16 v[122:125], v[160:163], v[168:171], v[122:125]
	v_mfma_f32_16x16x32_bf16 v[118:121], v[148:151], v[176:179], v[118:121]
	v_mfma_f32_16x16x32_bf16 v[110:113], v[160:163], v[176:179], v[110:113]
	v_mfma_f32_16x16x32_bf16 v[102:105], v[148:151], v[184:187], v[102:105]
	v_mfma_f32_16x16x32_bf16 v[94:97], v[160:163], v[184:187], v[94:97]
	v_mfma_f32_16x16x32_bf16 v[86:89], v[148:151], v[192:195], v[86:89]
	v_mfma_f32_16x16x32_bf16 v[78:81], v[160:163], v[192:195], v[78:81]
	s_barrier
	s_add_i32 s58, 16, 0x14000
	v_add_u32_e32 v152, s58, v145
	s_add_i32 s56, s56, s23
	ds_read_b128 v[196:199], v152
	ds_read_b128 v[200:203], v152 offset:1024
	ds_read_b128 v[204:207], v152 offset:2048
	ds_read_b128 v[208:211], v152 offset:3072
	v_lshl_add_u64 v[152:153], s[2:3], 0, v[32:33]
	s_mov_b32 m0, s56
	v_lshl_add_u64 v[212:213], s[2:3], 0, v[130:131]
	global_load_lds_dwordx4 v[152:153], off
	s_add_i32 m0, s56, 0x2000
	s_nop 0
	global_load_lds_dwordx4 v[212:213], off
	s_barrier
	s_waitcnt lgkmcnt(0)
	s_waitcnt lgkmcnt(0)
	v_mfma_f32_16x16x32_bf16 v[114:117], v[196:199], v[164:167], v[114:117]
	v_mfma_f32_16x16x32_bf16 v[106:109], v[204:207], v[164:167], v[106:109]
	v_mfma_f32_16x16x32_bf16 v[98:101], v[196:199], v[172:175], v[98:101]
	v_mfma_f32_16x16x32_bf16 v[90:93], v[204:207], v[172:175], v[90:93]
	v_mfma_f32_16x16x32_bf16 v[82:85], v[196:199], v[180:183], v[82:85]
	v_mfma_f32_16x16x32_bf16 v[74:77], v[204:207], v[180:183], v[74:77]
	v_mfma_f32_16x16x32_bf16 v[70:73], v[196:199], v[188:191], v[70:73]
	v_mfma_f32_16x16x32_bf16 v[66:69], v[204:207], v[188:191], v[66:69]
	v_mfma_f32_16x16x32_bf16 v[114:117], v[200:203], v[168:171], v[114:117]
	v_mfma_f32_16x16x32_bf16 v[106:109], v[208:211], v[168:171], v[106:109]
	v_mfma_f32_16x16x32_bf16 v[98:101], v[200:203], v[176:179], v[98:101]
	v_mfma_f32_16x16x32_bf16 v[90:93], v[208:211], v[176:179], v[90:93]
	v_mfma_f32_16x16x32_bf16 v[82:85], v[200:203], v[184:187], v[82:85]
	v_mfma_f32_16x16x32_bf16 v[74:77], v[208:211], v[184:187], v[74:77]
	v_mfma_f32_16x16x32_bf16 v[70:73], v[200:203], v[192:195], v[70:73]
	v_mfma_f32_16x16x32_bf16 v[66:69], v[208:211], v[192:195], v[66:69]
	s_mov_b32 m0, s26
	v_lshl_add_u64 v[214:215], s[20:21], 0, v[134:135]
	s_barrier
	ds_read_b128 v[164:167], v147 offset:16384
	ds_read_b128 v[168:171], v147 offset:17408
	ds_read_b128 v[172:175], v147 offset:18432
	ds_read_b128 v[176:179], v147 offset:19456
	ds_read_b128 v[180:183], v147 offset:20480
	ds_read_b128 v[184:187], v147 offset:21504
	ds_read_b128 v[188:191], v147 offset:22528
	ds_read_b128 v[192:195], v147 offset:23552
	global_load_lds_dwordx4 v[214:215], off
	v_lshl_add_u64 v[216:217], s[20:21], 0, v[132:133]
	s_mov_b32 m0, s27
	s_nop 0
	global_load_lds_dwordx4 v[216:217], off
	s_barrier
	s_waitcnt lgkmcnt(0)
	s_waitcnt lgkmcnt(0)
	v_mfma_f32_16x16x32_bf16 v[62:65], v[140:143], v[164:167], v[62:65]
	v_mfma_f32_16x16x32_bf16 v[58:61], v[156:159], v[164:167], v[58:61]
	v_mfma_f32_16x16x32_bf16 v[54:57], v[140:143], v[172:175], v[54:57]
	v_mfma_f32_16x16x32_bf16 v[46:49], v[156:159], v[172:175], v[46:49]
	v_mfma_f32_16x16x32_bf16 v[38:41], v[140:143], v[180:183], v[38:41]
	v_mfma_f32_16x16x32_bf16 v[28:31], v[156:159], v[180:183], v[28:31]
	v_mfma_f32_16x16x32_bf16 v[20:23], v[140:143], v[188:191], v[20:23]
	v_mfma_f32_16x16x32_bf16 v[12:15], v[156:159], v[188:191], v[12:15]
	v_mfma_f32_16x16x32_bf16 v[62:65], v[148:151], v[168:171], v[62:65]
	v_mfma_f32_16x16x32_bf16 v[58:61], v[160:163], v[168:171], v[58:61]
	v_mfma_f32_16x16x32_bf16 v[54:57], v[148:151], v[176:179], v[54:57]
	v_mfma_f32_16x16x32_bf16 v[46:49], v[160:163], v[176:179], v[46:49]
	v_mfma_f32_16x16x32_bf16 v[38:41], v[148:151], v[184:187], v[38:41]
	v_mfma_f32_16x16x32_bf16 v[28:31], v[160:163], v[184:187], v[28:31]
	v_mfma_f32_16x16x32_bf16 v[20:23], v[148:151], v[192:195], v[20:23]
	v_mfma_f32_16x16x32_bf16 v[12:15], v[160:163], v[192:195], v[12:15]
	s_barrier
	s_add_u32 s56, s2, 0x80000
	s_addc_u32 s57, s3, 0
	s_add_i32 s58, s58, s23
	v_lshl_add_u64 v[140:141], s[56:57], 0, v[32:33]
	s_mov_b32 m0, s58
	s_nop 0
	global_load_lds_dwordx4 v[140:141], off
	v_lshl_add_u64 v[140:141], s[56:57], 0, v[130:131]
	s_add_i32 m0, s58, 0x2000
	s_nop 0
	global_load_lds_dwordx4 v[140:141], off
	s_waitcnt vmcnt(6)
	s_barrier
	v_mfma_f32_16x16x32_bf16 v[50:53], v[196:199], v[164:167], v[50:53]
	v_mfma_f32_16x16x32_bf16 v[42:45], v[204:207], v[164:167], v[42:45]
	v_mfma_f32_16x16x32_bf16 v[34:37], v[196:199], v[172:175], v[34:37]
	v_mfma_f32_16x16x32_bf16 v[24:27], v[204:207], v[172:175], v[24:27]
	v_mfma_f32_16x16x32_bf16 v[16:19], v[196:199], v[180:183], v[16:19]
	v_mfma_f32_16x16x32_bf16 v[8:11], v[204:207], v[180:183], v[8:11]
	v_mfma_f32_16x16x32_bf16 v[4:7], v[196:199], v[188:191], v[4:7]
	v_mfma_f32_16x16x32_bf16 v[0:3], v[204:207], v[188:191], v[0:3]
	v_mfma_f32_16x16x32_bf16 v[50:53], v[200:203], v[168:171], v[50:53]
	v_mfma_f32_16x16x32_bf16 v[42:45], v[208:211], v[168:171], v[42:45]
	v_mfma_f32_16x16x32_bf16 v[34:37], v[200:203], v[176:179], v[34:37]
	v_mfma_f32_16x16x32_bf16 v[24:27], v[208:211], v[176:179], v[24:27]
	v_mfma_f32_16x16x32_bf16 v[16:19], v[200:203], v[184:187], v[16:19]
	v_mfma_f32_16x16x32_bf16 v[8:11], v[208:211], v[184:187], v[8:11]
	v_mfma_f32_16x16x32_bf16 v[4:7], v[200:203], v[192:195], v[4:7]
	v_mfma_f32_16x16x32_bf16 v[0:3], v[208:211], v[192:195], v[0:3]
	s_add_i32 s56, 16, 0x18000
	v_add_u32_e32 v155, s56, v145
	s_barrier
	ds_read_b128 v[140:143], v155
	ds_read_b128 v[148:151], v155 offset:1024
	ds_read_b128 v[156:159], v155 offset:2048
	ds_read_b128 v[160:163], v155 offset:3072
	s_add_u32 s20, s20, 0x80000
	s_addc_u32 s21, s21, 0
	s_mov_b32 m0, s28
	v_lshl_add_u64 v[196:197], s[20:21], 0, v[134:135]
	ds_read_b128 v[164:167], v147 offset:32768
	ds_read_b128 v[168:171], v147 offset:33792
	ds_read_b128 v[172:175], v147 offset:34816
	ds_read_b128 v[176:179], v147 offset:35840
	ds_read_b128 v[180:183], v147 offset:36864
	ds_read_b128 v[184:187], v147 offset:37888
	ds_read_b128 v[188:191], v147 offset:38912
	ds_read_b128 v[192:195], v147 offset:39936
	global_load_lds_dwordx4 v[196:197], off
	v_lshl_add_u64 v[196:197], s[20:21], 0, v[132:133]
	s_mov_b32 m0, s29
	s_nop 0
	global_load_lds_dwordx4 v[196:197], off
	s_waitcnt lgkmcnt(8)
	s_barrier
	s_waitcnt lgkmcnt(0)
	s_waitcnt lgkmcnt(0)
	v_mfma_f32_16x16x32_bf16 v[126:129], v[140:143], v[164:167], v[126:129]
	v_mfma_f32_16x16x32_bf16 v[122:125], v[156:159], v[164:167], v[122:125]
	v_mfma_f32_16x16x32_bf16 v[118:121], v[140:143], v[172:175], v[118:121]
	v_mfma_f32_16x16x32_bf16 v[110:113], v[156:159], v[172:175], v[110:113]
	v_mfma_f32_16x16x32_bf16 v[102:105], v[140:143], v[180:183], v[102:105]
	v_mfma_f32_16x16x32_bf16 v[94:97], v[156:159], v[180:183], v[94:97]
	v_mfma_f32_16x16x32_bf16 v[86:89], v[140:143], v[188:191], v[86:89]
	v_mfma_f32_16x16x32_bf16 v[78:81], v[156:159], v[188:191], v[78:81]
	v_mfma_f32_16x16x32_bf16 v[126:129], v[148:151], v[168:171], v[126:129]
	v_mfma_f32_16x16x32_bf16 v[122:125], v[160:163], v[168:171], v[122:125]
	v_mfma_f32_16x16x32_bf16 v[118:121], v[148:151], v[176:179], v[118:121]
	v_mfma_f32_16x16x32_bf16 v[110:113], v[160:163], v[176:179], v[110:113]
	v_mfma_f32_16x16x32_bf16 v[102:105], v[148:151], v[184:187], v[102:105]
	v_mfma_f32_16x16x32_bf16 v[94:97], v[160:163], v[184:187], v[94:97]
	v_mfma_f32_16x16x32_bf16 v[86:89], v[148:151], v[192:195], v[86:89]
	v_mfma_f32_16x16x32_bf16 v[78:81], v[160:163], v[192:195], v[78:81]
	s_barrier
	s_add_i32 s20, 16, 0x1c000
	s_add_i32 s21, s56, s23
	v_add_u32_e32 v155, s20, v145
	v_lshl_add_u64 v[152:153], v[152:153], 0, s[50:51]
	s_mov_b32 m0, s21
	ds_read_b128 v[196:199], v155
	ds_read_b128 v[200:203], v155 offset:1024
	ds_read_b128 v[204:207], v155 offset:2048
	ds_read_b128 v[208:211], v155 offset:3072
	global_load_lds_dwordx4 v[152:153], off
	v_lshl_add_u64 v[152:153], v[212:213], 0, s[50:51]
	s_add_i32 m0, s21, 0x2000
	s_nop 0
	global_load_lds_dwordx4 v[152:153], off
	s_barrier
	s_waitcnt lgkmcnt(0)
	s_waitcnt lgkmcnt(0)
	v_mfma_f32_16x16x32_bf16 v[114:117], v[196:199], v[164:167], v[114:117]
	v_mfma_f32_16x16x32_bf16 v[106:109], v[204:207], v[164:167], v[106:109]
	v_mfma_f32_16x16x32_bf16 v[98:101], v[196:199], v[172:175], v[98:101]
	v_mfma_f32_16x16x32_bf16 v[90:93], v[204:207], v[172:175], v[90:93]
	v_mfma_f32_16x16x32_bf16 v[82:85], v[196:199], v[180:183], v[82:85]
	v_mfma_f32_16x16x32_bf16 v[74:77], v[204:207], v[180:183], v[74:77]
	v_mfma_f32_16x16x32_bf16 v[70:73], v[196:199], v[188:191], v[70:73]
	v_mfma_f32_16x16x32_bf16 v[66:69], v[204:207], v[188:191], v[66:69]
	v_mfma_f32_16x16x32_bf16 v[114:117], v[200:203], v[168:171], v[114:117]
	v_mfma_f32_16x16x32_bf16 v[106:109], v[208:211], v[168:171], v[106:109]
	v_mfma_f32_16x16x32_bf16 v[98:101], v[200:203], v[176:179], v[98:101]
	v_mfma_f32_16x16x32_bf16 v[90:93], v[208:211], v[176:179], v[90:93]
	v_mfma_f32_16x16x32_bf16 v[82:85], v[200:203], v[184:187], v[82:85]
	v_mfma_f32_16x16x32_bf16 v[74:77], v[208:211], v[184:187], v[74:77]
	v_mfma_f32_16x16x32_bf16 v[70:73], v[200:203], v[192:195], v[70:73]
	v_mfma_f32_16x16x32_bf16 v[66:69], v[208:211], v[192:195], v[66:69]
	s_mov_b32 m0, s30
	v_lshl_add_u64 v[152:153], v[214:215], 0, s[50:51]
	s_barrier
	ds_read_b128 v[164:167], v147 offset:49152
	ds_read_b128 v[168:171], v147 offset:50176
	ds_read_b128 v[172:175], v147 offset:51200
	ds_read_b128 v[176:179], v147 offset:52224
	ds_read_b128 v[180:183], v147 offset:53248
	ds_read_b128 v[184:187], v147 offset:54272
	ds_read_b128 v[188:191], v147 offset:55296
	ds_read_b128 v[192:195], v147 offset:56320
	global_load_lds_dwordx4 v[152:153], off
	v_lshl_add_u64 v[152:153], v[216:217], 0, s[50:51]
	s_mov_b32 m0, s31
	s_nop 0
	global_load_lds_dwordx4 v[152:153], off
	s_barrier
	s_waitcnt lgkmcnt(0)
	s_waitcnt lgkmcnt(0)
	v_mfma_f32_16x16x32_bf16 v[62:65], v[140:143], v[164:167], v[62:65]
	v_mfma_f32_16x16x32_bf16 v[58:61], v[156:159], v[164:167], v[58:61]
	v_mfma_f32_16x16x32_bf16 v[54:57], v[140:143], v[172:175], v[54:57]
	v_mfma_f32_16x16x32_bf16 v[46:49], v[156:159], v[172:175], v[46:49]
	v_mfma_f32_16x16x32_bf16 v[38:41], v[140:143], v[180:183], v[38:41]
	v_mfma_f32_16x16x32_bf16 v[28:31], v[156:159], v[180:183], v[28:31]
	v_mfma_f32_16x16x32_bf16 v[20:23], v[140:143], v[188:191], v[20:23]
	v_mfma_f32_16x16x32_bf16 v[12:15], v[156:159], v[188:191], v[12:15]
	v_mfma_f32_16x16x32_bf16 v[62:65], v[148:151], v[168:171], v[62:65]
	v_mfma_f32_16x16x32_bf16 v[58:61], v[160:163], v[168:171], v[58:61]
	v_mfma_f32_16x16x32_bf16 v[54:57], v[148:151], v[176:179], v[54:57]
	v_mfma_f32_16x16x32_bf16 v[46:49], v[160:163], v[176:179], v[46:49]
	v_mfma_f32_16x16x32_bf16 v[38:41], v[148:151], v[184:187], v[38:41]
	v_mfma_f32_16x16x32_bf16 v[28:31], v[160:163], v[184:187], v[28:31]
	v_mfma_f32_16x16x32_bf16 v[20:23], v[148:151], v[192:195], v[20:23]
	v_mfma_f32_16x16x32_bf16 v[12:15], v[160:163], v[192:195], v[12:15]
	s_barrier
	s_add_u32 s2, s2, 0x80080
	s_addc_u32 s3, s3, 0
	s_add_i32 s20, s20, s23
	v_lshl_add_u64 v[140:141], s[2:3], 0, v[32:33]
	s_mov_b32 m0, s20
	s_nop 0
	global_load_lds_dwordx4 v[140:141], off
	v_lshl_add_u64 v[140:141], s[2:3], 0, v[130:131]
	s_add_i32 m0, s20, 0x2000
	s_nop 0
	global_load_lds_dwordx4 v[140:141], off
	s_waitcnt vmcnt(6)
	s_barrier
	v_mfma_f32_16x16x32_bf16 v[50:53], v[196:199], v[164:167], v[50:53]
	v_mfma_f32_16x16x32_bf16 v[42:45], v[204:207], v[164:167], v[42:45]
	v_mfma_f32_16x16x32_bf16 v[34:37], v[196:199], v[172:175], v[34:37]
	v_mfma_f32_16x16x32_bf16 v[24:27], v[204:207], v[172:175], v[24:27]
	v_mfma_f32_16x16x32_bf16 v[16:19], v[196:199], v[180:183], v[16:19]
	v_mfma_f32_16x16x32_bf16 v[8:11], v[204:207], v[180:183], v[8:11]
	v_mfma_f32_16x16x32_bf16 v[4:7], v[196:199], v[188:191], v[4:7]
	v_mfma_f32_16x16x32_bf16 v[0:3], v[204:207], v[188:191], v[0:3]
	v_mfma_f32_16x16x32_bf16 v[50:53], v[200:203], v[168:171], v[50:53]
	v_mfma_f32_16x16x32_bf16 v[42:45], v[208:211], v[168:171], v[42:45]
	v_mfma_f32_16x16x32_bf16 v[34:37], v[200:203], v[176:179], v[34:37]
	v_mfma_f32_16x16x32_bf16 v[24:27], v[208:211], v[176:179], v[24:27]
	v_mfma_f32_16x16x32_bf16 v[16:19], v[200:203], v[184:187], v[16:19]
	v_mfma_f32_16x16x32_bf16 v[8:11], v[208:211], v[184:187], v[8:11]
	v_mfma_f32_16x16x32_bf16 v[4:7], v[200:203], v[192:195], v[4:7]
	v_mfma_f32_16x16x32_bf16 v[0:3], v[208:211], v[192:195], v[0:3]
	s_add_i32 s47, s47, 2
	s_add_u32 s39, s39, 0x100
	s_addc_u32 s46, s46, 0
	s_add_u32 s18, s18, 0x100
	s_addc_u32 s19, s19, 0
	s_cmp_gt_u32 s47, 29
	s_barrier
	s_cbranch_scc0 .LBB0_1104
	v_lshl_add_u32 v150, s36, 8, v144
	v_lshl_or_b32 v142, s35, 8, v146
	v_ashrrev_i32_e32 v143, 31, v142
	v_mov_b64_e32 v[140:141], s[8:9]
	s_movk_i32 s11, 0x5800
	v_cvt_pk_bf16_f32 v70, v70, v71
	v_cvt_pk_bf16_f32 v71, v72, v73
	v_cvt_pk_bf16_f32 v72, v66, v67
	v_add_u32_e32 v66, 0x80, v150
	v_mad_i64_i32 v[148:149], s[2:3], v150, s11, v[140:141]
	v_lshlrev_b64 v[142:143], 1, v[142:143]
	v_cvt_pk_bf16_f32 v114, v114, v115
	v_cvt_pk_bf16_f32 v115, v116, v117
	v_cvt_pk_bf16_f32 v116, v106, v107
	v_or_b32_e32 v106, 16, v150
	v_mad_i64_i32 v[66:67], s[2:3], v66, s11, v[140:141]
	v_cvt_pk_bf16_f32 v50, v50, v51
	v_cvt_pk_bf16_f32 v51, v52, v53
	v_cvt_pk_bf16_f32 v52, v42, v43
	v_add_u32_e32 v42, 0x90, v150
	v_lshl_add_u64 v[148:149], v[148:149], 0, v[142:143]
	v_mad_i64_i32 v[106:107], s[2:3], v106, s11, v[140:141]
	v_cvt_pk_bf16_f32 v98, v98, v99
	v_cvt_pk_bf16_f32 v99, v100, v101
	v_cvt_pk_bf16_f32 v100, v90, v91
	v_or_b32_e32 v90, 32, v150
	v_lshl_add_u64 v[66:67], v[66:67], 0, v[142:143]
	v_mad_i64_i32 v[42:43], s[2:3], v42, s11, v[140:141]
	v_cvt_pk_bf16_f32 v34, v34, v35
	v_cvt_pk_bf16_f32 v35, v36, v37
	v_cvt_pk_bf16_f32 v36, v24, v25
	v_add_u32_e32 v24, 0xa0, v150
	v_cvt_pk_bf16_f32 v117, v108, v109
	global_store_dwordx4 v[148:149], v[114:117], off offset:256
	v_mad_i64_i32 v[90:91], s[2:3], v90, s11, v[140:141]
	s_nop 0
	v_lshl_add_u64 v[114:115], v[106:107], 0, v[142:143]
	v_cvt_pk_bf16_f32 v82, v82, v83
	v_cvt_pk_bf16_f32 v83, v84, v85
	v_cvt_pk_bf16_f32 v84, v74, v75
	v_or_b32_e32 v74, 48, v150
	v_cvt_pk_bf16_f32 v53, v44, v45
	global_store_dwordx4 v[66:67], v[50:53], off offset:256
	v_mad_i64_i32 v[24:25], s[2:3], v24, s11, v[140:141]
	s_nop 0
	v_lshl_add_u64 v[50:51], v[42:43], 0, v[142:143]
	v_cvt_pk_bf16_f32 v16, v16, v17
	v_cvt_pk_bf16_f32 v17, v18, v19
	v_cvt_pk_bf16_f32 v18, v8, v9
	v_add_u32_e32 v8, 0xb0, v150
	v_cvt_pk_bf16_f32 v101, v92, v93
	global_store_dwordx4 v[114:115], v[98:101], off offset:256
	v_mad_i64_i32 v[74:75], s[2:3], v74, s11, v[140:141]
	s_nop 0
	v_lshl_add_u64 v[98:99], v[90:91], 0, v[142:143]
	v_cvt_pk_bf16_f32 v37, v26, v27
	global_store_dwordx4 v[50:51], v[34:37], off offset:256
	v_mad_i64_i32 v[8:9], s[2:3], v8, s11, v[140:141]
	s_nop 0
	v_lshl_add_u64 v[34:35], v[24:25], 0, v[142:143]
	v_cvt_pk_bf16_f32 v85, v76, v77
	global_store_dwordx4 v[98:99], v[82:85], off offset:256
	v_cvt_pk_bf16_f32 v19, v10, v11
	global_store_dwordx4 v[34:35], v[16:19], off offset:256
	s_and_b64 vcc, exec, s[4:5]
	v_lshl_add_u64 v[82:83], v[74:75], 0, v[142:143]
	v_lshl_add_u64 v[16:17], v[8:9], 0, v[142:143]
	s_mov_b32 s35, s10
	s_mov_b32 s36, s12
	s_mov_b64 s[18:19], s[16:17]
	s_mov_b64 s[20:21], s[14:15]
	v_cvt_pk_bf16_f32 v126, v126, v127
	v_cvt_pk_bf16_f32 v127, v128, v129
	v_cvt_pk_bf16_f32 v128, v122, v123
	v_cvt_pk_bf16_f32 v129, v124, v125
	global_store_dwordx4 v[148:149], v[126:129], off
	v_cvt_pk_bf16_f32 v106, v118, v119
	v_cvt_pk_bf16_f32 v107, v120, v121
	v_cvt_pk_bf16_f32 v108, v110, v111
	v_cvt_pk_bf16_f32 v109, v112, v113
	global_store_dwordx4 v[114:115], v[106:109], off
	v_cvt_pk_bf16_f32 v90, v102, v103
	v_cvt_pk_bf16_f32 v91, v104, v105
	v_cvt_pk_bf16_f32 v92, v94, v95
	v_cvt_pk_bf16_f32 v93, v96, v97
	global_store_dwordx4 v[98:99], v[90:93], off
	v_cvt_pk_bf16_f32 v74, v86, v87
	v_cvt_pk_bf16_f32 v75, v88, v89
	v_cvt_pk_bf16_f32 v76, v78, v79
	v_cvt_pk_bf16_f32 v77, v80, v81
	global_store_dwordx4 v[82:83], v[74:77], off
	v_cvt_pk_bf16_f32 v73, v68, v69
	global_store_dwordx4 v[82:83], v[70:73], off offset:256
	v_cvt_pk_bf16_f32 v62, v62, v63
	v_cvt_pk_bf16_f32 v63, v64, v65
	v_cvt_pk_bf16_f32 v64, v58, v59
	v_cvt_pk_bf16_f32 v65, v60, v61
	global_store_dwordx4 v[66:67], v[62:65], off
	v_cvt_pk_bf16_f32 v42, v54, v55
	v_cvt_pk_bf16_f32 v43, v56, v57
	v_cvt_pk_bf16_f32 v44, v46, v47
	v_cvt_pk_bf16_f32 v45, v48, v49
	global_store_dwordx4 v[50:51], v[42:45], off
	v_cvt_pk_bf16_f32 v24, v38, v39
	v_cvt_pk_bf16_f32 v25, v40, v41
	v_cvt_pk_bf16_f32 v26, v28, v29
	v_cvt_pk_bf16_f32 v27, v30, v31
	global_store_dwordx4 v[34:35], v[24:27], off
	v_cvt_pk_bf16_f32 v8, v20, v21
	v_cvt_pk_bf16_f32 v9, v22, v23
	v_cvt_pk_bf16_f32 v10, v12, v13
	v_cvt_pk_bf16_f32 v11, v14, v15
	global_store_dwordx4 v[16:17], v[8:11], off
	v_cvt_pk_bf16_f32 v4, v4, v5
	v_cvt_pk_bf16_f32 v5, v6, v7
	v_cvt_pk_bf16_f32 v6, v0, v1
	v_cvt_pk_bf16_f32 v7, v2, v3
	global_store_dwordx4 v[16:17], v[4:7], off offset:256
	s_cbranch_vccz .LBB0_1101
	s_waitcnt vmcnt(0)
	s_cmpk_gt_u32 s22, 0xff
	s_cbranch_scc1 .LBB0_1108
	s_barrier

.LBB0_1109:
	s_setprio 0
	v_readlane_b32 s0, v253, 8
	v_readlane_b32 s1, v253, 9
	v_readlane_b32 s2, v253, 10
	v_readlane_b32 s3, v253, 11
	v_readlane_b32 s4, v253, 12
	v_readlane_b32 s5, v253, 13
	s_mov_b64 s[0:1], s[2:3]
	s_mov_b64 s[46:47], s[4:5]
	s_getreg_b32 s0, hwreg(HW_REG_XCC_ID, 0, 4)
	s_waitcnt vmcnt(0)
	v_readlane_b32 s6, v253, 14
	v_readlane_b32 s7, v253, 15
	s_waitcnt vmcnt(0) lgkmcnt(0)
	s_barrier
	s_mov_b64 s[78:79], exec
	v_readlane_b32 s2, v253, 0
	v_readlane_b32 s3, v253, 1
	s_and_b64 s[2:3], s[78:79], s[2:3]
	s_mov_b64 exec, s[2:3]
	s_cbranch_execz .LBB0_1153
	s_waitcnt vmcnt(0) expcnt(0) lgkmcnt(0)
	ds_read_b32 v2, v33
	ds_read_b32 v0, v33 offset:4
	s_and_b32 s66, s0, 15
	s_waitcnt lgkmcnt(1)
	v_cmp_ne_u32_e32 vcc, 0, v2
	s_cbranch_vccnz .LBB0_1124
	s_add_u32 s0, s46, 0x300ae900
	s_addc_u32 s1, s47, 0
	s_add_u32 s4, s46, 0x300aeb00
	s_addc_u32 s5, s47, 0
	s_add_u32 s6, s46, 0x300aec00
	s_addc_u32 s7, s47, 0
	s_add_u32 s8, s46, 0x300aed00
	s_addc_u32 s9, s47, 0
	s_add_u32 s10, s46, 0x300aee00
	s_addc_u32 s11, s47, 0
	s_add_u32 s12, s46, 0x300aef00
	s_addc_u32 s13, s47, 0
	s_add_u32 s14, s46, 0x300af000
	s_addc_u32 s15, s47, 0
	s_add_u32 s16, s46, 0x300af100
	s_addc_u32 s17, s47, 0
	s_add_u32 s18, s46, 0x300af200
	s_addc_u32 s19, s47, 0
	s_add_u32 s20, s46, 0x300af300
	s_addc_u32 s21, s47, 0
	s_add_u32 s22, s46, 0x300af400
	s_addc_u32 s23, s47, 0
	s_add_u32 s28, s46, 0x300af500
	s_addc_u32 s29, s47, 0
	s_add_u32 s30, s46, 0x300af600
	s_addc_u32 s31, s47, 0
	s_add_u32 s34, s46, 0x300af700
	s_addc_u32 s35, s47, 0
	s_add_u32 s36, s46, 0x300af800
	s_addc_u32 s37, s47, 0
	s_add_u32 s60, s46, 0x300af900
	s_addc_u32 s61, s47, 0
	s_add_u32 s2, s46, 0x300afa00
	s_addc_u32 s3, s47, 0
	s_mov_b32 s86, 1
	s_mov_b64 s[64:65], 0
	s_branch .LBB0_1114

.LBB0_1249:
	s_or_b64 exec, exec, s[78:79]
	v_readlane_b32 s0, v253, 8
	v_readlane_b32 s1, v253, 9
	v_readlane_b32 s2, v253, 10
	v_readlane_b32 s3, v253, 11
	v_readlane_b32 s4, v253, 12
	v_readlane_b32 s5, v253, 13
	v_readlane_b32 s6, v253, 14
	v_readlane_b32 s7, v253, 15
	s_mov_b64 s[0:1], s[4:5]
	s_mov_b64 s[6:7], s[2:3]
	s_waitcnt lgkmcnt(0)
	s_barrier
	s_add_u32 s8, s0, 0xc402c00
	s_addc_u32 s9, s1, 0
	s_add_u32 s10, s0, 0x4e00000
	s_addc_u32 s11, s1, 0
	v_mov_b32_e32 v16, v224
	s_and_b64 vcc, exec, s[76:77]
	v_readfirstlane_b32 s22, v16
	s_cbranch_vccnz .LBB0_1267
	v_lshlrev_b32_e32 v0, 4, v16
	v_add_u32_e32 v1, 0x2000, v0
	v_ashrrev_i32_e32 v2, 31, v1
	v_lshrrev_b32_e32 v2, 22, v2
	v_add_u32_e32 v2, v1, v2
	v_ashrrev_i32_e32 v9, 10, v2
	v_lshlrev_b32_e32 v2, 5, v9
	v_and_b32_e32 v8, 32, v2
	v_mul_i32_i24_e32 v2, 0x400, v9
	v_sub_u32_e32 v1, v1, v2
	v_lshrrev_b32_e32 v2, 4, v1
	v_bitop3_b32 v1, v2, v1, 32 bitop3:0x6c
	v_ashrrev_i32_e32 v2, 31, v1
	v_lshrrev_b32_e32 v2, 26, v2
	v_add_u32_e32 v2, v1, v2
	v_ashrrev_i32_e32 v11, 6, v2
	v_and_b32_e32 v2, 0xc0, v2
	v_sub_u32_e32 v1, v1, v2
	v_ashrrev_i16_sdwa v1, v226, sext(v1) dst_sel:DWORD dst_unused:UNUSED_PAD src0_sel:DWORD src1_sel:BYTE_0
	v_bfe_i32 v10, v1, 0, 16
	v_lshlrev_b32_e32 v1, 3, v9
	v_and_b32_e32 v1, 0x7ffff0, v1
	v_add_u32_e32 v1, v11, v1
	s_movk_i32 s4, 0x1600
	v_mul_lo_u32 v1, v1, s4
	v_add3_u32 v2, v8, v10, v1
	s_waitcnt vmcnt(0)
	v_add_lshl_u32 v132, v2, v1, 1
	v_ashrrev_i32_e32 v1, 31, v16
	v_lshrrev_b32_e32 v1, 26, v1
	v_add_u32_e32 v1, v16, v1
	v_ashrrev_i32_e32 v13, 6, v1
	v_lshlrev_b32_e32 v1, 5, v13
	v_and_b32_e32 v12, 32, v1
	v_bfe_i32 v1, v16, 27, 1
	v_lshrrev_b32_e32 v1, 22, v1
	v_add_u32_e32 v1, v0, v1
	v_and_b32_e32 v1, 0xfffffc00, v1
	v_sub_u32_e32 v0, v0, v1
	v_lshrrev_b32_e32 v1, 4, v0
	v_bitop3_b32 v1, v1, v0, 32 bitop3:0x6c
	v_ashrrev_i32_e32 v0, 31, v0
	v_lshrrev_b32_e32 v0, 26, v0
	v_add_u32_e32 v0, v1, v0
	v_ashrrev_i32_e32 v15, 6, v0
	v_mul_i32_i24_e32 v0, 64, v15
	v_sub_u32_e32 v0, v1, v0
	v_ashrrev_i16_sdwa v0, v226, sext(v0) dst_sel:DWORD dst_unused:UNUSED_PAD src0_sel:DWORD src1_sel:BYTE_0
	v_bfe_i32 v14, v0, 0, 16
	v_lshlrev_b32_e32 v0, 3, v13
	v_and_b32_e32 v0, 0x7ffff0, v0
	s_ashr_i32 s2, s22, 6
	v_add_u32_e32 v0, v15, v0
	v_readlane_b32 s5, v254, 44
	s_ashr_i32 s3, s22, 8
	s_lshl_b32 s23, s2, 10
	v_mul_lo_u32 v0, v0, s4
	s_mul_i32 s4, s5, 0x2c0000
	s_add_u32 s16, s10, s4
	s_mul_hi_i32 s4, s5, 0x2c0000
	v_add3_u32 v1, v12, v14, v0
	s_addc_u32 s17, s11, s4
	s_add_i32 s26, s23, 16
	v_lshlrev_b32_e32 v32, 1, v1
	s_add_i32 m0, s26, 0x10000
	v_readlane_b32 s4, v254, 45
	global_load_lds_dwordx4 v32, s[16:17]
	s_add_i32 m0, s26, 0x12000
	s_mov_b32 s12, s4
	s_mul_i32 s4, s4, 0x580000
	v_lshlrev_b32_e32 v130, 1, v2
	s_add_u32 s14, s8, s4
	s_mul_hi_i32 s4, s12, 0x580000
	v_add_lshl_u32 v134, v1, v0, 1
	global_load_lds_dwordx4 v130, s[16:17]
	s_addc_u32 s15, s9, s4
	s_mov_b32 m0, s26
	s_add_i32 s27, s26, 0x2000
	v_readlane_b32 s5, v254, 46
	global_load_lds_dwordx4 v134, s[14:15]
	s_mov_b32 m0, s27
	s_add_u32 s4, s16, 0x160000
	global_load_lds_dwordx4 v132, s[14:15]
	s_addc_u32 s5, s17, 0
	s_add_i32 m0, s26, 0x14000
	v_mov_b32_e32 v131, v33
	global_load_lds_dwordx4 v32, s[4:5]
	s_add_i32 m0, s26, 0x16000
	v_mov_b32_e32 v135, v33
	global_load_lds_dwordx4 v130, s[4:5]
	s_add_u32 s4, s14, 0x2c0000
	s_addc_u32 s5, s15, 0
	s_add_i32 s28, s26, 0x4000
	s_mov_b32 m0, s28
	s_add_i32 s29, s26, 0x6000
	global_load_lds_dwordx4 v134, s[4:5]
	s_mov_b32 m0, s29
	v_mov_b32_e32 v133, v33
	global_load_lds_dwordx4 v132, s[4:5]
	v_lshl_add_u64 v[6:7], s[16:17], 0, v[32:33]
	v_lshl_add_u64 v[4:5], s[16:17], 0, v[130:131]
	v_lshl_add_u64 v[2:3], s[14:15], 0, v[134:135]
	s_cmp_lg_u32 s3, 1
	v_lshl_add_u64 v[0:1], s[14:15], 0, v[132:133]
	s_cbranch_scc1 .LBB0_1252
	s_setprio 1
	s_barrier

.LBB0_1261:
	s_add_u32 s16, s14, 0x100
	s_addc_u32 s17, s15, 0
	s_add_i32 s58, 16, 0x10000
	v_add_u32_e32 v152, s58, v174
	ds_read_b128 v[140:143], v152
	ds_read_b128 v[144:147], v152 offset:1024
	ds_read_b128 v[148:151], v152 offset:2048
	ds_read_b128 v[156:159], v152 offset:3072
	s_cmpk_eq_i32 s57, 0x54
	s_cselect_b32 s21, s1, s17
	s_cselect_b32 s20, s0, s16
	s_cselect_b32 s19, s5, s56
	s_cselect_b32 s18, s4, s47
	v_lshl_add_u64 v[152:153], s[14:15], 0, v[138:139]
	s_add_i32 m0, s26, 0xc000
	ds_read_b128 v[160:163], v176
	ds_read_b128 v[164:167], v176 offset:1024
	ds_read_b128 v[168:171], v176 offset:2048
	ds_read_b128 v[178:181], v176 offset:3072
	ds_read_b128 v[182:185], v176 offset:4096
	ds_read_b128 v[186:189], v176 offset:5120
	ds_read_b128 v[190:193], v176 offset:6144
	ds_read_b128 v[194:197], v176 offset:7168
	global_load_lds_dwordx4 v[152:153], off
	v_lshl_add_u64 v[152:153], s[14:15], 0, v[136:137]
	s_add_i32 m0, s26, 0xe000
	s_nop 0
	global_load_lds_dwordx4 v[152:153], off
	s_waitcnt lgkmcnt(8)
	s_barrier
	s_waitcnt lgkmcnt(0)
	s_waitcnt lgkmcnt(0)
	v_mfma_f32_16x16x32_bf16 v[126:129], v[140:143], v[160:163], v[126:129]
	v_mfma_f32_16x16x32_bf16 v[122:125], v[148:151], v[160:163], v[122:125]
	v_mfma_f32_16x16x32_bf16 v[110:113], v[140:143], v[168:171], v[110:113]
	v_mfma_f32_16x16x32_bf16 v[106:109], v[148:151], v[168:171], v[106:109]
	v_mfma_f32_16x16x32_bf16 v[102:105], v[140:143], v[182:185], v[102:105]
	v_mfma_f32_16x16x32_bf16 v[98:101], v[148:151], v[182:185], v[98:101]
	v_mfma_f32_16x16x32_bf16 v[78:81], v[140:143], v[190:193], v[78:81]
	v_mfma_f32_16x16x32_bf16 v[74:77], v[148:151], v[190:193], v[74:77]
	v_mfma_f32_16x16x32_bf16 v[126:129], v[144:147], v[164:167], v[126:129]
	v_mfma_f32_16x16x32_bf16 v[122:125], v[156:159], v[164:167], v[122:125]
	v_mfma_f32_16x16x32_bf16 v[110:113], v[144:147], v[178:181], v[110:113]
	v_mfma_f32_16x16x32_bf16 v[106:109], v[156:159], v[178:181], v[106:109]
	v_mfma_f32_16x16x32_bf16 v[102:105], v[144:147], v[186:189], v[102:105]
	v_mfma_f32_16x16x32_bf16 v[98:101], v[156:159], v[186:189], v[98:101]
	v_mfma_f32_16x16x32_bf16 v[78:81], v[144:147], v[194:197], v[78:81]
	v_mfma_f32_16x16x32_bf16 v[74:77], v[156:159], v[194:197], v[74:77]
	s_barrier
	s_add_i32 s59, 16, 0x14000
	v_add_u32_e32 v152, s59, v174
	s_add_i32 s14, s58, s23
	ds_read_b128 v[198:201], v152
	ds_read_b128 v[202:205], v152 offset:1024
	ds_read_b128 v[206:209], v152 offset:2048
	ds_read_b128 v[210:213], v152 offset:3072
	v_lshl_add_u64 v[152:153], s[18:19], 0, v[32:33]
	s_mov_b32 m0, s14
	v_lshl_add_u64 v[172:173], s[18:19], 0, v[130:131]
	global_load_lds_dwordx4 v[152:153], off
	s_add_i32 m0, s14, 0x2000
	s_nop 0
	global_load_lds_dwordx4 v[172:173], off
	s_barrier
	s_waitcnt lgkmcnt(0)
	s_waitcnt lgkmcnt(0)
	v_mfma_f32_16x16x32_bf16 v[118:121], v[198:201], v[160:163], v[118:121]
	v_mfma_f32_16x16x32_bf16 v[114:117], v[206:209], v[160:163], v[114:117]
	v_mfma_f32_16x16x32_bf16 v[94:97], v[198:201], v[168:171], v[94:97]
	v_mfma_f32_16x16x32_bf16 v[90:93], v[206:209], v[168:171], v[90:93]
	v_mfma_f32_16x16x32_bf16 v[86:89], v[198:201], v[182:185], v[86:89]
	v_mfma_f32_16x16x32_bf16 v[82:85], v[206:209], v[182:185], v[82:85]
	v_mfma_f32_16x16x32_bf16 v[70:73], v[198:201], v[190:193], v[70:73]
	v_mfma_f32_16x16x32_bf16 v[66:69], v[206:209], v[190:193], v[66:69]
	v_mfma_f32_16x16x32_bf16 v[118:121], v[202:205], v[164:167], v[118:121]
	v_mfma_f32_16x16x32_bf16 v[114:117], v[210:213], v[164:167], v[114:117]
	v_mfma_f32_16x16x32_bf16 v[94:97], v[202:205], v[178:181], v[94:97]
	v_mfma_f32_16x16x32_bf16 v[90:93], v[210:213], v[178:181], v[90:93]
	v_mfma_f32_16x16x32_bf16 v[86:89], v[202:205], v[186:189], v[86:89]
	v_mfma_f32_16x16x32_bf16 v[82:85], v[210:213], v[186:189], v[82:85]
	v_mfma_f32_16x16x32_bf16 v[70:73], v[202:205], v[194:197], v[70:73]
	v_mfma_f32_16x16x32_bf16 v[66:69], v[210:213], v[194:197], v[66:69]
	s_mov_b32 m0, s26
	v_lshl_add_u64 v[214:215], s[20:21], 0, v[134:135]
	s_barrier
	ds_read_b128 v[160:163], v176 offset:16384
	ds_read_b128 v[164:167], v176 offset:17408
	ds_read_b128 v[168:171], v176 offset:18432
	ds_read_b128 v[178:181], v176 offset:19456
	ds_read_b128 v[182:185], v176 offset:20480
	ds_read_b128 v[186:189], v176 offset:21504
	ds_read_b128 v[190:193], v176 offset:22528
	ds_read_b128 v[194:197], v176 offset:23552
	global_load_lds_dwordx4 v[214:215], off
	v_lshl_add_u64 v[216:217], s[20:21], 0, v[132:133]
	s_mov_b32 m0, s27
	s_nop 0
	global_load_lds_dwordx4 v[216:217], off
	s_barrier
	s_waitcnt lgkmcnt(0)
	s_waitcnt lgkmcnt(0)
	v_mfma_f32_16x16x32_bf16 v[62:65], v[140:143], v[160:163], v[62:65]
	v_mfma_f32_16x16x32_bf16 v[58:61], v[148:151], v[160:163], v[58:61]
	v_mfma_f32_16x16x32_bf16 v[46:49], v[140:143], v[168:171], v[46:49]
	v_mfma_f32_16x16x32_bf16 v[42:45], v[148:151], v[168:171], v[42:45]
	v_mfma_f32_16x16x32_bf16 v[38:41], v[140:143], v[182:185], v[38:41]
	v_mfma_f32_16x16x32_bf16 v[28:31], v[148:151], v[182:185], v[28:31]
	v_mfma_f32_16x16x32_bf16 v[20:23], v[140:143], v[190:193], v[20:23]
	v_mfma_f32_16x16x32_bf16 v[12:15], v[148:151], v[190:193], v[12:15]
	v_mfma_f32_16x16x32_bf16 v[62:65], v[144:147], v[164:167], v[62:65]
	v_mfma_f32_16x16x32_bf16 v[58:61], v[156:159], v[164:167], v[58:61]
	v_mfma_f32_16x16x32_bf16 v[46:49], v[144:147], v[178:181], v[46:49]
	v_mfma_f32_16x16x32_bf16 v[42:45], v[156:159], v[178:181], v[42:45]
	v_mfma_f32_16x16x32_bf16 v[38:41], v[144:147], v[186:189], v[38:41]
	v_mfma_f32_16x16x32_bf16 v[28:31], v[156:159], v[186:189], v[28:31]
	v_mfma_f32_16x16x32_bf16 v[20:23], v[144:147], v[194:197], v[20:23]
	v_mfma_f32_16x16x32_bf16 v[12:15], v[156:159], v[194:197], v[12:15]
	s_barrier
	s_add_u32 s14, s18, 0x160000
	s_addc_u32 s15, s19, 0
	s_add_i32 s58, s59, s23
	v_lshl_add_u64 v[140:141], s[14:15], 0, v[32:33]
	s_mov_b32 m0, s58
	s_nop 0
	global_load_lds_dwordx4 v[140:141], off
	v_lshl_add_u64 v[140:141], s[14:15], 0, v[130:131]
	s_add_i32 m0, s58, 0x2000
	s_nop 0
	global_load_lds_dwordx4 v[140:141], off
	s_waitcnt vmcnt(6)
	s_barrier
	v_mfma_f32_16x16x32_bf16 v[54:57], v[198:201], v[160:163], v[54:57]
	v_mfma_f32_16x16x32_bf16 v[50:53], v[206:209], v[160:163], v[50:53]
	v_mfma_f32_16x16x32_bf16 v[34:37], v[198:201], v[168:171], v[34:37]
	v_mfma_f32_16x16x32_bf16 v[24:27], v[206:209], v[168:171], v[24:27]
	v_mfma_f32_16x16x32_bf16 v[16:19], v[198:201], v[182:185], v[16:19]
	v_mfma_f32_16x16x32_bf16 v[8:11], v[206:209], v[182:185], v[8:11]
	v_mfma_f32_16x16x32_bf16 v[4:7], v[198:201], v[190:193], v[4:7]
	v_mfma_f32_16x16x32_bf16 v[0:3], v[206:209], v[190:193], v[0:3]
	v_mfma_f32_16x16x32_bf16 v[54:57], v[202:205], v[164:167], v[54:57]
	v_mfma_f32_16x16x32_bf16 v[50:53], v[210:213], v[164:167], v[50:53]
	v_mfma_f32_16x16x32_bf16 v[34:37], v[202:205], v[178:181], v[34:37]
	v_mfma_f32_16x16x32_bf16 v[24:27], v[210:213], v[178:181], v[24:27]
	v_mfma_f32_16x16x32_bf16 v[16:19], v[202:205], v[186:189], v[16:19]
	v_mfma_f32_16x16x32_bf16 v[8:11], v[210:213], v[186:189], v[8:11]
	v_mfma_f32_16x16x32_bf16 v[4:7], v[202:205], v[194:197], v[4:7]
	v_mfma_f32_16x16x32_bf16 v[0:3], v[210:213], v[194:197], v[0:3]
	s_add_i32 s58, 16, 0x18000
	v_add_u32_e32 v156, s58, v174
	s_barrier
	ds_read_b128 v[140:143], v156
	ds_read_b128 v[144:147], v156 offset:1024
	ds_read_b128 v[148:151], v156 offset:2048
	ds_read_b128 v[156:159], v156 offset:3072
	s_add_u32 s14, s20, 0x2c0000
	s_addc_u32 s15, s21, 0
	s_mov_b32 m0, s28
	v_lshl_add_u64 v[198:199], s[14:15], 0, v[134:135]
	ds_read_b128 v[160:163], v176 offset:32768
	ds_read_b128 v[164:167], v176 offset:33792
	ds_read_b128 v[168:171], v176 offset:34816
	ds_read_b128 v[178:181], v176 offset:35840
	ds_read_b128 v[182:185], v176 offset:36864
	ds_read_b128 v[186:189], v176 offset:37888
	ds_read_b128 v[190:193], v176 offset:38912
	ds_read_b128 v[194:197], v176 offset:39936
	global_load_lds_dwordx4 v[198:199], off
	v_lshl_add_u64 v[198:199], s[14:15], 0, v[132:133]
	s_mov_b32 m0, s29
	s_nop 0
	global_load_lds_dwordx4 v[198:199], off
	s_waitcnt lgkmcnt(8)
	s_barrier
	s_waitcnt lgkmcnt(0)
	s_waitcnt lgkmcnt(0)
	v_mfma_f32_16x16x32_bf16 v[126:129], v[140:143], v[160:163], v[126:129]
	v_mfma_f32_16x16x32_bf16 v[122:125], v[148:151], v[160:163], v[122:125]
	v_mfma_f32_16x16x32_bf16 v[110:113], v[140:143], v[168:171], v[110:113]
	v_mfma_f32_16x16x32_bf16 v[106:109], v[148:151], v[168:171], v[106:109]
	v_mfma_f32_16x16x32_bf16 v[102:105], v[140:143], v[182:185], v[102:105]
	v_mfma_f32_16x16x32_bf16 v[98:101], v[148:151], v[182:185], v[98:101]
	v_mfma_f32_16x16x32_bf16 v[78:81], v[140:143], v[190:193], v[78:81]
	v_mfma_f32_16x16x32_bf16 v[74:77], v[148:151], v[190:193], v[74:77]
	v_mfma_f32_16x16x32_bf16 v[126:129], v[144:147], v[164:167], v[126:129]
	v_mfma_f32_16x16x32_bf16 v[122:125], v[156:159], v[164:167], v[122:125]
	v_mfma_f32_16x16x32_bf16 v[110:113], v[144:147], v[178:181], v[110:113]
	v_mfma_f32_16x16x32_bf16 v[106:109], v[156:159], v[178:181], v[106:109]
	v_mfma_f32_16x16x32_bf16 v[102:105], v[144:147], v[186:189], v[102:105]
	v_mfma_f32_16x16x32_bf16 v[98:101], v[156:159], v[186:189], v[98:101]
	v_mfma_f32_16x16x32_bf16 v[78:81], v[144:147], v[194:197], v[78:81]
	v_mfma_f32_16x16x32_bf16 v[74:77], v[156:159], v[194:197], v[74:77]
	s_barrier
	s_add_i32 s20, 16, 0x1c000
	s_add_i32 s14, s58, s23
	v_add_u32_e32 v177, s20, v174
	v_lshl_add_u64 v[152:153], v[152:153], 0, s[50:51]
	s_mov_b32 m0, s14
	ds_read_b128 v[198:201], v177
	ds_read_b128 v[202:205], v177 offset:1024
	ds_read_b128 v[206:209], v177 offset:2048
	ds_read_b128 v[210:213], v177 offset:3072
	global_load_lds_dwordx4 v[152:153], off
	v_lshl_add_u64 v[152:153], v[172:173], 0, s[50:51]
	s_add_i32 m0, s14, 0x2000
	s_nop 0
	global_load_lds_dwordx4 v[152:153], off
	s_barrier
	s_waitcnt lgkmcnt(0)
	s_waitcnt lgkmcnt(0)
	v_mfma_f32_16x16x32_bf16 v[118:121], v[198:201], v[160:163], v[118:121]
	v_mfma_f32_16x16x32_bf16 v[114:117], v[206:209], v[160:163], v[114:117]
	v_mfma_f32_16x16x32_bf16 v[94:97], v[198:201], v[168:171], v[94:97]
	v_mfma_f32_16x16x32_bf16 v[90:93], v[206:209], v[168:171], v[90:93]
	v_mfma_f32_16x16x32_bf16 v[86:89], v[198:201], v[182:185], v[86:89]
	v_mfma_f32_16x16x32_bf16 v[82:85], v[206:209], v[182:185], v[82:85]
	v_mfma_f32_16x16x32_bf16 v[70:73], v[198:201], v[190:193], v[70:73]
	v_mfma_f32_16x16x32_bf16 v[66:69], v[206:209], v[190:193], v[66:69]
	v_mfma_f32_16x16x32_bf16 v[118:121], v[202:205], v[164:167], v[118:121]
	v_mfma_f32_16x16x32_bf16 v[114:117], v[210:213], v[164:167], v[114:117]
	v_mfma_f32_16x16x32_bf16 v[94:97], v[202:205], v[178:181], v[94:97]
	v_mfma_f32_16x16x32_bf16 v[90:93], v[210:213], v[178:181], v[90:93]
	v_mfma_f32_16x16x32_bf16 v[86:89], v[202:205], v[186:189], v[86:89]
	v_mfma_f32_16x16x32_bf16 v[82:85], v[210:213], v[186:189], v[82:85]
	v_mfma_f32_16x16x32_bf16 v[70:73], v[202:205], v[194:197], v[70:73]
	v_mfma_f32_16x16x32_bf16 v[66:69], v[210:213], v[194:197], v[66:69]
	s_mov_b32 m0, s34
	v_lshl_add_u64 v[152:153], v[214:215], 0, s[50:51]
	s_barrier
	ds_read_b128 v[160:163], v176 offset:49152
	ds_read_b128 v[164:167], v176 offset:50176
	ds_read_b128 v[168:171], v176 offset:51200
	ds_read_b128 v[178:181], v176 offset:52224
	ds_read_b128 v[182:185], v176 offset:53248
	ds_read_b128 v[186:189], v176 offset:54272
	ds_read_b128 v[190:193], v176 offset:55296
	ds_read_b128 v[194:197], v176 offset:56320
	global_load_lds_dwordx4 v[152:153], off
	v_lshl_add_u64 v[152:153], v[216:217], 0, s[50:51]
	s_mov_b32 m0, s35
	s_nop 0
	global_load_lds_dwordx4 v[152:153], off
	s_barrier
	s_waitcnt lgkmcnt(0)
	s_waitcnt lgkmcnt(0)
	v_mfma_f32_16x16x32_bf16 v[62:65], v[140:143], v[160:163], v[62:65]
	v_mfma_f32_16x16x32_bf16 v[58:61], v[148:151], v[160:163], v[58:61]
	v_mfma_f32_16x16x32_bf16 v[46:49], v[140:143], v[168:171], v[46:49]
	v_mfma_f32_16x16x32_bf16 v[42:45], v[148:151], v[168:171], v[42:45]
	v_mfma_f32_16x16x32_bf16 v[38:41], v[140:143], v[182:185], v[38:41]
	v_mfma_f32_16x16x32_bf16 v[28:31], v[148:151], v[182:185], v[28:31]
	v_mfma_f32_16x16x32_bf16 v[20:23], v[140:143], v[190:193], v[20:23]
	v_mfma_f32_16x16x32_bf16 v[12:15], v[148:151], v[190:193], v[12:15]
	v_mfma_f32_16x16x32_bf16 v[62:65], v[144:147], v[164:167], v[62:65]
	v_mfma_f32_16x16x32_bf16 v[58:61], v[156:159], v[164:167], v[58:61]
	v_mfma_f32_16x16x32_bf16 v[46:49], v[144:147], v[178:181], v[46:49]
	v_mfma_f32_16x16x32_bf16 v[42:45], v[156:159], v[178:181], v[42:45]
	v_mfma_f32_16x16x32_bf16 v[38:41], v[144:147], v[186:189], v[38:41]
	v_mfma_f32_16x16x32_bf16 v[28:31], v[156:159], v[186:189], v[28:31]
	v_mfma_f32_16x16x32_bf16 v[20:23], v[144:147], v[194:197], v[20:23]
	v_mfma_f32_16x16x32_bf16 v[12:15], v[156:159], v[194:197], v[12:15]
	s_barrier
	s_add_u32 s14, s18, 0x160080
	s_addc_u32 s15, s19, 0
	s_add_i32 s18, s20, s23
	v_lshl_add_u64 v[140:141], s[14:15], 0, v[32:33]
	s_mov_b32 m0, s18
	s_nop 0
	global_load_lds_dwordx4 v[140:141], off
	v_lshl_add_u64 v[140:141], s[14:15], 0, v[130:131]
	s_add_i32 m0, s18, 0x2000
	s_nop 0
	global_load_lds_dwordx4 v[140:141], off
	s_waitcnt vmcnt(6)
	s_barrier
	v_mfma_f32_16x16x32_bf16 v[54:57], v[198:201], v[160:163], v[54:57]
	v_mfma_f32_16x16x32_bf16 v[50:53], v[206:209], v[160:163], v[50:53]
	v_mfma_f32_16x16x32_bf16 v[34:37], v[198:201], v[168:171], v[34:37]
	v_mfma_f32_16x16x32_bf16 v[24:27], v[206:209], v[168:171], v[24:27]
	v_mfma_f32_16x16x32_bf16 v[16:19], v[198:201], v[182:185], v[16:19]
	v_mfma_f32_16x16x32_bf16 v[8:11], v[206:209], v[182:185], v[8:11]
	v_mfma_f32_16x16x32_bf16 v[4:7], v[198:201], v[190:193], v[4:7]
	v_mfma_f32_16x16x32_bf16 v[0:3], v[206:209], v[190:193], v[0:3]
	v_mfma_f32_16x16x32_bf16 v[54:57], v[202:205], v[164:167], v[54:57]
	v_mfma_f32_16x16x32_bf16 v[50:53], v[210:213], v[164:167], v[50:53]
	v_mfma_f32_16x16x32_bf16 v[34:37], v[202:205], v[178:181], v[34:37]
	v_mfma_f32_16x16x32_bf16 v[24:27], v[210:213], v[178:181], v[24:27]
	v_mfma_f32_16x16x32_bf16 v[16:19], v[202:205], v[186:189], v[16:19]
	v_mfma_f32_16x16x32_bf16 v[8:11], v[210:213], v[186:189], v[8:11]
	v_mfma_f32_16x16x32_bf16 v[4:7], v[202:205], v[194:197], v[4:7]
	v_mfma_f32_16x16x32_bf16 v[0:3], v[210:213], v[194:197], v[0:3]
	s_add_i32 s57, s57, 2
	s_add_u32 s47, s47, 0x100
	s_addc_u32 s56, s56, 0
	s_cmpk_gt_u32 s57, 0x55
	s_mov_b64 s[14:15], s[16:17]
	s_barrier
	s_cbranch_scc0 .LBB0_1261
	s_cmp_lt_i32 s46, 32
	s_mov_b64 s[14:15], 0xc000
	s_cbranch_scc1 .LBB0_1253
	s_sub_i32 s14, s46, 32
	s_lshr_b32 s14, s14, 4
	s_mul_hi_u32 s15, s14, 0x3000
	s_mulk_i32 s14, 0x3000
	s_branch .LBB0_1253

.LBB0_1267:
	s_setprio 0
	v_readlane_b32 s0, v253, 8
	v_readlane_b32 s1, v253, 9
	v_readlane_b32 s2, v253, 10
	v_readlane_b32 s3, v253, 11
	v_readlane_b32 s4, v253, 12
	v_readlane_b32 s5, v253, 13
	s_mov_b64 s[38:39], s[4:5]
	s_mov_b64 s[0:1], s[2:3]
	s_getreg_b32 s0, hwreg(HW_REG_XCC_ID, 0, 4)
	s_waitcnt vmcnt(0)
	v_readlane_b32 s6, v253, 14
	v_readlane_b32 s7, v253, 15
	s_waitcnt lgkmcnt(0)
	s_barrier
	s_mov_b64 s[30:31], exec
	v_readlane_b32 s2, v253, 0
	v_readlane_b32 s3, v253, 1
	v_readlane_b32 s76, v254, 0
	s_and_b64 s[2:3], s[30:31], s[2:3]
	v_readlane_b32 s77, v254, 1
	v_readlane_b32 s78, v254, 2
	v_readlane_b32 s79, v254, 3
	v_readlane_b32 s80, v254, 4
	v_readlane_b32 s81, v254, 5
	v_readlane_b32 s82, v254, 6
	v_readlane_b32 s83, v254, 7
	v_readlane_b32 s88, v254, 12
	v_readlane_b32 s89, v254, 13
	v_readlane_b32 s90, v254, 14
	v_readlane_b32 s91, v254, 15
	v_readlane_b32 s84, v254, 8
	v_readlane_b32 s85, v254, 9
	v_readlane_b32 s86, v254, 10
	v_readlane_b32 s87, v254, 11
	s_mov_b64 exec, s[2:3]
	s_cbranch_execnz .LBB0_1268
	s_getpc_b64 s[98:99]
